# FFN-up epilogue: store-only vmcnt(0) waits relaxed to vmcnt(6)
# speedup vs baseline: 1.0222x; 1.0025x over previous
; __device__ __forceinline__ unsigned cvt_pk_bf16(float lo, float hi) { const f32x2_t v = {lo, hi}; const bf16x2_t b = __builtin_convertvector(v, bf16x2_t); return __builtin_bit_cast(unsigned, b); }
; template <int N> __device__ __forceinline__ float dpp_ror(float v) { return __builtin_bit_cast(float, __builtin_amdgcn_update_dpp(0, __builtin_bit_cast(int, v), 0x120 + N, 0xf, 0xf, false)); }
;     __device__ __forceinline__ void operator()(const Acc& acc, const Unit& u, int wr, int wc, int fr, int fq) const {
;     ...
;                 for (int m = 0; m < 4; ++m) {
;                     const int rt = ai * 128 + wr * 64 + m * 16 + fr;
;                     const f32x4 g = acc[ai][0][m][n], up = acc[ai][1][m][n];
;                     const f32x4 gp = (m == 0) ? hg : acc[ai][0][m == 0 ? 0 : m - 1][n], upp = (m == 0) ? hu : acc[ai][1][m == 0 ? 0 : m - 1][n];
;                     f32x4 g1, g2, u1, u2;
; #pragma unroll
;                     for (int j = 0; j < 4; ++j) {
;                         g1[j] = dpp_ror<1>((fr == 15) ? gp[j] : g[j]); g2[j] = dpp_ror<2>((fr >= 14) ? gp[j] : g[j]);
;                         u1[j] = dpp_ror<1>((fr == 15) ? upp[j] : up[j]); u2[j] = dpp_ror<2>((fr >= 14) ? upp[j] : up[j]);
;                     }
;                     const f32x4 hcg = gb + gw0 * g2 + gw1 * g1 + gw2 * g, hcu = ub + uw0 * u2 + uw1 * u1 + uw2 * up;
;                     f32x4 a;
; #pragma unroll
;                     for (int j = 0; j < 4; ++j) a[j] = hcg[j] * __builtin_amdgcn_rcpf(1.f + __builtin_amdgcn_exp2f(-1.4426950408889634f * hcg[j])) * hcu[j];
;                     if (rt >= 2) { u32x2 w; w.x = cvt_pk_bf16(a[0], a[1]); w.y = cvt_pk_bf16(a[2], a[3]); *(u32x2*)(act + ((size_t)u.pm * 256 + rt) * DFF + ch) = w; }
.LBB0_694:
	s_or_b64 exec, exec, s[18:19]
	v_cndmask_b32_e64 v0, v150, v158, s[42:43]
	v_cndmask_b32_e64 v244, v150, v158, s[40:41]
	v_cndmask_b32_e64 v245, v146, v154, s[42:43]
	v_mov_b32_dpp v208, v0 row_ror:1 row_mask:0xf bank_mask:0xf
	v_mov_b32_dpp v210, v244 row_ror:2 row_mask:0xf bank_mask:0xf
	v_mov_b32_dpp v166, v245 row_ror:1 row_mask:0xf bank_mask:0xf
	v_cndmask_b32_e64 v0, v146, v154, s[40:41]
	v_cndmask_b32_e64 v244, v151, v159, s[42:43]
	v_cndmask_b32_e64 v245, v151, v159, s[40:41]
	v_mov_b32_dpp v168, v0 row_ror:2 row_mask:0xf bank_mask:0xf
	v_mov_b32_dpp v209, v244 row_ror:1 row_mask:0xf bank_mask:0xf
	s_andn2_b64 vcc, exec, s[20:21]
	v_mov_b32_dpp v211, v245 row_ror:2 row_mask:0xf bank_mask:0xf
	v_cndmask_b32_e64 v0, v147, v155, s[42:43]
	v_cndmask_b32_e64 v244, v147, v155, s[40:41]
	v_lshl_add_u64 v[154:155], s[16:17], 0, v[182:183]
	v_mov_b32_dpp v167, v0 row_ror:1 row_mask:0xf bank_mask:0xf
	v_mov_b32_dpp v169, v244 row_ror:2 row_mask:0xf bank_mask:0xf
	v_cndmask_b32_e64 v245, v152, v160, s[42:43]
	v_cndmask_b32_e64 v0, v152, v160, s[40:41]
	v_cndmask_b32_e64 v244, v148, v156, s[42:43]
	v_mov_b32_dpp v164, v245 row_ror:1 row_mask:0xf bank_mask:0xf
	v_mov_b32_dpp v160, v0 row_ror:2 row_mask:0xf bank_mask:0xf
	v_mov_b32_dpp v158, v244 row_ror:1 row_mask:0xf bank_mask:0xf
	v_cndmask_b32_e64 v245, v148, v156, s[40:41]
	v_cndmask_b32_e64 v0, v153, v161, s[42:43]
	v_cndmask_b32_e64 v244, v153, v161, s[40:41]
	v_mov_b32_dpp v156, v245 row_ror:2 row_mask:0xf bank_mask:0xf
	v_mov_b32_dpp v165, v0 row_ror:1 row_mask:0xf bank_mask:0xf
	v_mov_b32_dpp v161, v244 row_ror:2 row_mask:0xf bank_mask:0xf
	v_cndmask_b32_e64 v245, v149, v157, s[42:43]
	v_cndmask_b32_e64 v0, v149, v157, s[40:41]
	s_nop 0
	v_mov_b32_dpp v159, v245 row_ror:1 row_mask:0xf bank_mask:0xf
	v_mov_b32_dpp v157, v0 row_ror:2 row_mask:0xf bank_mask:0xf
	v_cndmask_b32_e64 v0, 0, 1, s[20:21]
	v_cmp_ne_u32_e64 s[56:57], 1, v0
	s_cbranch_vccnz .LBB0_696
	s_waitcnt vmcnt(4)
	v_pk_fma_f32 v[210:211], v[130:131], v[210:211], v[142:143]
	v_pk_fma_f32 v[160:161], v[132:133], v[160:161], v[144:145]
	v_pk_fma_f32 v[208:209], v[134:135], v[208:209], v[210:211]
	v_pk_fma_f32 v[160:161], v[136:137], v[164:165], v[160:161]
	v_pk_fma_f32 v[208:209], v[150:151], v[138:139], v[208:209]
	v_pk_fma_f32 v[160:161], v[152:153], v[140:141], v[160:161]
	v_mul_f32_e32 v0, 0xbfb8aa3b, v208
	v_mul_f32_e32 v210, 0xbfb8aa3b, v209
	v_exp_f32_e32 v0, v0
	v_exp_f32_e32 v210, v210
	s_waitcnt vmcnt(6)
	v_pk_fma_f32 v[168:169], v[114:115], v[168:169], v[126:127]
	v_mul_f32_e32 v164, 0xbfb8aa3b, v161
	v_add_f32_e32 v0, 1.0, v0
	v_add_f32_e32 v211, 1.0, v210
	v_rcp_f32_e32 v210, v0
	v_rcp_f32_e32 v211, v211
	v_mul_f32_e32 v0, 0xbfb8aa3b, v160
	v_exp_f32_e32 v0, v0
	v_pk_fma_f32 v[166:167], v[118:119], v[166:167], v[168:169]
	v_pk_mul_f32 v[168:169], v[208:209], v[210:211]
	v_exp_f32_e32 v208, v164
	v_pk_fma_f32 v[166:167], v[146:147], v[122:123], v[166:167]
	v_add_f32_e32 v0, 1.0, v0
	v_pk_mul_f32 v[164:165], v[166:167], v[168:169]
	v_rcp_f32_e32 v166, v0
	v_add_f32_e32 v0, 1.0, v208
	v_rcp_f32_e32 v167, v0
	v_pk_fma_f32 v[156:157], v[116:117], v[156:157], v[128:129]
	s_nop 0
	v_pk_fma_f32 v[156:157], v[120:121], v[158:159], v[156:157]
	v_pk_mul_f32 v[158:159], v[160:161], v[166:167]
	v_pk_fma_f32 v[156:157], v[148:149], v[124:125], v[156:157]
	s_nop 0
	v_pk_mul_f32 v[156:157], v[156:157], v[158:159]
	v_cvt_pk_bf16_f32 v158, v164, v165
	v_cvt_pk_bf16_f32 v159, v156, v157
	v_mov_b64_e32 v[156:157], s[12:13]
	v_mad_u64_u32 v[156:157], s[18:19], v154, s60, v[156:157]
	v_mad_i32_i24 v157, v155, s60, v157
	v_lshl_add_u64 v[156:157], v[202:203], 1, v[156:157]
	global_store_dwordx2 v[156:157], v[158:159], off
.LBB0_696:
	v_cndmask_b32_e64 v0, v110, v150, s[42:43]
	v_cndmask_b32_e64 v244, v110, v150, s[40:41]
	v_cndmask_b32_e64 v245, v106, v146, s[42:43]
	v_mov_b32_dpp v164, v0 row_ror:1 row_mask:0xf bank_mask:0xf
	v_mov_b32_dpp v166, v244 row_ror:2 row_mask:0xf bank_mask:0xf
	v_mov_b32_dpp v158, v245 row_ror:1 row_mask:0xf bank_mask:0xf
	v_cndmask_b32_e64 v0, v106, v146, s[40:41]
	v_cndmask_b32_e64 v244, v111, v151, s[42:43]
	v_cndmask_b32_e64 v245, v111, v151, s[40:41]
	v_mov_b32_dpp v160, v0 row_ror:2 row_mask:0xf bank_mask:0xf
	v_mov_b32_dpp v165, v244 row_ror:1 row_mask:0xf bank_mask:0xf
	s_and_b64 vcc, exec, s[56:57]
	v_mov_b32_dpp v167, v245 row_ror:2 row_mask:0xf bank_mask:0xf
	v_cndmask_b32_e64 v0, v107, v147, s[42:43]
	v_cndmask_b32_e64 v244, v107, v147, s[40:41]
	v_lshl_add_u64 v[146:147], s[16:17], 0, v[184:185]
	v_mov_b32_dpp v159, v0 row_ror:1 row_mask:0xf bank_mask:0xf
	v_mov_b32_dpp v161, v244 row_ror:2 row_mask:0xf bank_mask:0xf
	v_cndmask_b32_e64 v245, v112, v152, s[42:43]
	v_cndmask_b32_e64 v0, v112, v152, s[40:41]
	v_cndmask_b32_e64 v244, v108, v148, s[42:43]
	v_mov_b32_dpp v156, v245 row_ror:1 row_mask:0xf bank_mask:0xf
	v_mov_b32_dpp v152, v0 row_ror:2 row_mask:0xf bank_mask:0xf
	v_mov_b32_dpp v150, v244 row_ror:1 row_mask:0xf bank_mask:0xf
	v_cndmask_b32_e64 v245, v108, v148, s[40:41]
	v_cndmask_b32_e64 v0, v113, v153, s[42:43]
	v_cndmask_b32_e64 v244, v113, v153, s[40:41]
	v_mov_b32_dpp v148, v245 row_ror:2 row_mask:0xf bank_mask:0xf
	v_mov_b32_dpp v157, v0 row_ror:1 row_mask:0xf bank_mask:0xf
	v_mov_b32_dpp v153, v244 row_ror:2 row_mask:0xf bank_mask:0xf
	v_cndmask_b32_e64 v245, v109, v149, s[42:43]
	v_cndmask_b32_e64 v0, v109, v149, s[40:41]
	s_nop 0
	v_mov_b32_dpp v151, v245 row_ror:1 row_mask:0xf bank_mask:0xf
	v_mov_b32_dpp v149, v0 row_ror:2 row_mask:0xf bank_mask:0xf
	s_cbranch_vccnz .LBB0_698
; __device__ __forceinline__ unsigned cvt_pk_bf16(float lo, float hi) { const f32x2_t v = {lo, hi}; const bf16x2_t b = __builtin_convertvector(v, bf16x2_t); return __builtin_bit_cast(unsigned, b); }
; template <int N> __device__ __forceinline__ float dpp_ror(float v) { return __builtin_bit_cast(float, __builtin_amdgcn_update_dpp(0, __builtin_bit_cast(int, v), 0x120 + N, 0xf, 0xf, false)); }
;     __device__ __forceinline__ void operator()(const Acc& acc, const Unit& u, int wr, int wc, int fr, int fq) const {
;     ...
;                 for (int m = 0; m < 4; ++m) {
;                     const int rt = ai * 128 + wr * 64 + m * 16 + fr;
;                     const f32x4 g = acc[ai][0][m][n], up = acc[ai][1][m][n];
;                     const f32x4 gp = (m == 0) ? hg : acc[ai][0][m == 0 ? 0 : m - 1][n], upp = (m == 0) ? hu : acc[ai][1][m == 0 ? 0 : m - 1][n];
;                     f32x4 g1, g2, u1, u2;
; #pragma unroll
;                     for (int j = 0; j < 4; ++j) {
;                         g1[j] = dpp_ror<1>((fr == 15) ? gp[j] : g[j]); g2[j] = dpp_ror<2>((fr >= 14) ? gp[j] : g[j]);
;                         u1[j] = dpp_ror<1>((fr == 15) ? upp[j] : up[j]); u2[j] = dpp_ror<2>((fr >= 14) ? upp[j] : up[j]);
;                     }
;                     const f32x4 hcg = gb + gw0 * g2 + gw1 * g1 + gw2 * g, hcu = ub + uw0 * u2 + uw1 * u1 + uw2 * up;
;                     f32x4 a;
; #pragma unroll
;                     for (int j = 0; j < 4; ++j) a[j] = hcg[j] * __builtin_amdgcn_rcpf(1.f + __builtin_amdgcn_exp2f(-1.4426950408889634f * hcg[j])) * hcu[j];
;                     if (rt >= 2) { u32x2 w; w.x = cvt_pk_bf16(a[0], a[1]); w.y = cvt_pk_bf16(a[2], a[3]); *(u32x2*)(act + ((size_t)u.pm * 256 + rt) * DFF + ch) = w; }
	s_waitcnt vmcnt(4)
	v_pk_fma_f32 v[166:167], v[130:131], v[166:167], v[142:143]
	v_pk_fma_f32 v[152:153], v[132:133], v[152:153], v[144:145]
	v_pk_fma_f32 v[164:165], v[134:135], v[164:165], v[166:167]
	v_pk_fma_f32 v[152:153], v[136:137], v[156:157], v[152:153]
	v_pk_fma_f32 v[164:165], v[110:111], v[138:139], v[164:165]
	v_pk_fma_f32 v[152:153], v[112:113], v[140:141], v[152:153]
	v_mul_f32_e32 v0, 0xbfb8aa3b, v164
	v_mul_f32_e32 v166, 0xbfb8aa3b, v165
	v_exp_f32_e32 v0, v0
	v_exp_f32_e32 v166, v166
	s_waitcnt vmcnt(6)
	v_pk_fma_f32 v[160:161], v[114:115], v[160:161], v[126:127]
	v_mul_f32_e32 v156, 0xbfb8aa3b, v153
	v_add_f32_e32 v0, 1.0, v0
	v_add_f32_e32 v167, 1.0, v166
	v_rcp_f32_e32 v166, v0
	v_rcp_f32_e32 v167, v167
	v_mul_f32_e32 v0, 0xbfb8aa3b, v152
	v_exp_f32_e32 v0, v0
	v_pk_fma_f32 v[158:159], v[118:119], v[158:159], v[160:161]
	v_pk_mul_f32 v[160:161], v[164:165], v[166:167]
	v_exp_f32_e32 v164, v156
	v_pk_fma_f32 v[158:159], v[106:107], v[122:123], v[158:159]
	v_add_f32_e32 v0, 1.0, v0
	v_pk_mul_f32 v[156:157], v[158:159], v[160:161]
	v_rcp_f32_e32 v158, v0
	v_add_f32_e32 v0, 1.0, v164
	v_rcp_f32_e32 v159, v0
	v_pk_fma_f32 v[148:149], v[116:117], v[148:149], v[128:129]
	s_nop 0
	v_pk_fma_f32 v[148:149], v[120:121], v[150:151], v[148:149]
	v_pk_mul_f32 v[150:151], v[152:153], v[158:159]
	v_pk_fma_f32 v[148:149], v[108:109], v[124:125], v[148:149]
	s_nop 0
	v_pk_mul_f32 v[148:149], v[148:149], v[150:151]
	v_cvt_pk_bf16_f32 v150, v156, v157
	v_cvt_pk_bf16_f32 v151, v148, v149
	v_mov_b64_e32 v[148:149], s[12:13]
	v_mad_u64_u32 v[148:149], s[18:19], v146, s60, v[148:149]
	v_mad_i32_i24 v149, v147, s60, v149
	v_lshl_add_u64 v[148:149], v[202:203], 1, v[148:149]
	global_store_dwordx2 v[148:149], v[150:151], off
.LBB0_698:
	v_cndmask_b32_e64 v0, v102, v110, s[42:43]
	v_cndmask_b32_e64 v244, v102, v110, s[40:41]
	v_cndmask_b32_e64 v245, v98, v106, s[42:43]
	v_mov_b32_dpp v156, v0 row_ror:1 row_mask:0xf bank_mask:0xf
	v_mov_b32_dpp v158, v244 row_ror:2 row_mask:0xf bank_mask:0xf
	v_mov_b32_dpp v148, v245 row_ror:1 row_mask:0xf bank_mask:0xf
	v_cndmask_b32_e64 v0, v98, v106, s[40:41]
	v_cndmask_b32_e64 v244, v103, v111, s[42:43]
	v_cndmask_b32_e64 v245, v103, v111, s[40:41]
	v_mov_b32_dpp v152, v0 row_ror:2 row_mask:0xf bank_mask:0xf
	v_mov_b32_dpp v157, v244 row_ror:1 row_mask:0xf bank_mask:0xf
	v_mov_b32_dpp v159, v245 row_ror:2 row_mask:0xf bank_mask:0xf
	v_cndmask_b32_e64 v0, v99, v107, s[42:43]
	s_and_b64 vcc, exec, s[56:57]
	v_cndmask_b32_e64 v244, v99, v107, s[40:41]
	v_mov_b32_dpp v149, v0 row_ror:1 row_mask:0xf bank_mask:0xf
	v_cndmask_b32_e64 v245, v104, v112, s[42:43]
	v_mov_b32_dpp v153, v244 row_ror:2 row_mask:0xf bank_mask:0xf
	v_cndmask_b32_e64 v0, v104, v112, s[40:41]
	v_mov_b32_dpp v110, v245 row_ror:1 row_mask:0xf bank_mask:0xf
	v_cndmask_b32_e64 v244, v100, v108, s[42:43]
	v_mov_b32_dpp v150, v0 row_ror:2 row_mask:0xf bank_mask:0xf
	v_cndmask_b32_e64 v245, v100, v108, s[40:41]
	v_mov_b32_dpp v106, v244 row_ror:1 row_mask:0xf bank_mask:0xf
	v_cndmask_b32_e64 v0, v105, v113, s[42:43]
	v_mov_b32_dpp v108, v245 row_ror:2 row_mask:0xf bank_mask:0xf
	v_cndmask_b32_e64 v244, v105, v113, s[40:41]
	v_mov_b32_dpp v111, v0 row_ror:1 row_mask:0xf bank_mask:0xf
	v_lshl_add_u64 v[112:113], s[16:17], 0, v[186:187]
	v_mov_b32_dpp v151, v244 row_ror:2 row_mask:0xf bank_mask:0xf
	v_cndmask_b32_e64 v245, v101, v109, s[42:43]
	v_cndmask_b32_e64 v0, v101, v109, s[40:41]
	s_nop 0
	v_mov_b32_dpp v107, v245 row_ror:1 row_mask:0xf bank_mask:0xf
	v_mov_b32_dpp v109, v0 row_ror:2 row_mask:0xf bank_mask:0xf
	s_cbranch_vccnz .LBB0_700
	s_waitcnt vmcnt(4)
	v_pk_fma_f32 v[158:159], v[130:131], v[158:159], v[142:143]
	s_waitcnt vmcnt(6)
	v_pk_fma_f32 v[152:153], v[114:115], v[152:153], v[126:127]
	v_pk_fma_f32 v[156:157], v[134:135], v[156:157], v[158:159]
	v_pk_fma_f32 v[148:149], v[118:119], v[148:149], v[152:153]
	v_pk_fma_f32 v[102:103], v[102:103], v[138:139], v[156:157]
	v_pk_fma_f32 v[98:99], v[98:99], v[122:123], v[148:149]
	v_mul_f32_e32 v0, 0xbfb8aa3b, v102
	v_exp_f32_e32 v0, v0
	v_mul_f32_e32 v156, 0xbfb8aa3b, v103
	v_exp_f32_e32 v156, v156
	v_pk_fma_f32 v[148:149], v[132:133], v[150:151], v[144:145]
	v_add_f32_e32 v0, 1.0, v0
	v_pk_fma_f32 v[110:111], v[136:137], v[110:111], v[148:149]
	v_add_f32_e32 v157, 1.0, v156
	v_pk_fma_f32 v[104:105], v[104:105], v[140:141], v[110:111]
	v_rcp_f32_e32 v156, v0
	v_mul_f32_e32 v0, 0xbfb8aa3b, v104
	v_rcp_f32_e32 v157, v157
	v_exp_f32_e32 v0, v0
	v_mul_f32_e32 v110, 0xbfb8aa3b, v105
	v_exp_f32_e32 v110, v110
	v_pk_mul_f32 v[102:103], v[102:103], v[156:157]
	v_add_f32_e32 v0, 1.0, v0
	v_pk_mul_f32 v[98:99], v[98:99], v[102:103]
	v_rcp_f32_e32 v102, v0
	v_add_f32_e32 v0, 1.0, v110
	v_rcp_f32_e32 v103, v0
	v_pk_fma_f32 v[108:109], v[116:117], v[108:109], v[128:129]
	v_cvt_pk_bf16_f32 v98, v98, v99
	v_pk_fma_f32 v[106:107], v[120:121], v[106:107], v[108:109]
	v_pk_mul_f32 v[102:103], v[104:105], v[102:103]
	v_pk_fma_f32 v[100:101], v[100:101], v[124:125], v[106:107]
	s_nop 0
	v_pk_mul_f32 v[100:101], v[100:101], v[102:103]
	s_nop 0
	v_cvt_pk_bf16_f32 v99, v100, v101
	v_mov_b64_e32 v[100:101], s[12:13]
	v_mad_u64_u32 v[100:101], s[18:19], v112, s60, v[100:101]
	v_mad_i32_i24 v101, v113, s60, v101
	v_lshl_add_u64 v[100:101], v[202:203], 1, v[100:101]
	global_store_dwordx2 v[100:101], v[98:99], off

; __device__ __forceinline__ unsigned cvt_pk_bf16(float lo, float hi) { const f32x2_t v = {lo, hi}; const bf16x2_t b = __builtin_convertvector(v, bf16x2_t); return __builtin_bit_cast(unsigned, b); }
; template <int N> __device__ __forceinline__ float dpp_ror(float v) { return __builtin_bit_cast(float, __builtin_amdgcn_update_dpp(0, __builtin_bit_cast(int, v), 0x120 + N, 0xf, 0xf, false)); }
;     __device__ __forceinline__ void operator()(const Acc& acc, const Unit& u, int wr, int wc, int fr, int fq) const {
;     ...
;                 for (int m = 0; m < 4; ++m) {
;                     const int rt = ai * 128 + wr * 64 + m * 16 + fr;
;                     const f32x4 g = acc[ai][0][m][n], up = acc[ai][1][m][n];
;                     const f32x4 gp = (m == 0) ? hg : acc[ai][0][m == 0 ? 0 : m - 1][n], upp = (m == 0) ? hu : acc[ai][1][m == 0 ? 0 : m - 1][n];
;                     f32x4 g1, g2, u1, u2;
; #pragma unroll
;                     for (int j = 0; j < 4; ++j) {
;                         g1[j] = dpp_ror<1>((fr == 15) ? gp[j] : g[j]); g2[j] = dpp_ror<2>((fr >= 14) ? gp[j] : g[j]);
;                         u1[j] = dpp_ror<1>((fr == 15) ? upp[j] : up[j]); u2[j] = dpp_ror<2>((fr >= 14) ? upp[j] : up[j]);
;                     }
;                     const f32x4 hcg = gb + gw0 * g2 + gw1 * g1 + gw2 * g, hcu = ub + uw0 * u2 + uw1 * u1 + uw2 * up;
;                     f32x4 a;
; #pragma unroll
;                     for (int j = 0; j < 4; ++j) a[j] = hcg[j] * __builtin_amdgcn_rcpf(1.f + __builtin_amdgcn_exp2f(-1.4426950408889634f * hcg[j])) * hcu[j];
;                     if (rt >= 2) { u32x2 w; w.x = cvt_pk_bf16(a[0], a[1]); w.y = cvt_pk_bf16(a[2], a[3]); *(u32x2*)(act + ((size_t)u.pm * 256 + rt) * DFF + ch) = w; }
.LBB0_702:
	s_or_b64 exec, exec, s[18:19]
	s_waitcnt lgkmcnt(1)
	v_cndmask_b32_e64 v0, v94, v98, s[42:43]
	v_cndmask_b32_e64 v244, v94, v98, s[40:41]
	s_waitcnt lgkmcnt(0)
	v_mov_b32_dpp v150, v0 row_ror:1 row_mask:0xf bank_mask:0xf
	v_mov_b32_dpp v152, v244 row_ror:2 row_mask:0xf bank_mask:0xf
	v_cndmask_b32_e64 v245, v90, v102, s[42:43]
	v_cndmask_b32_e64 v0, v90, v102, s[40:41]
	v_cndmask_b32_e64 v244, v95, v99, s[42:43]
	v_mov_b32_dpp v108, v245 row_ror:1 row_mask:0xf bank_mask:0xf
	v_mov_b32_dpp v148, v0 row_ror:2 row_mask:0xf bank_mask:0xf
	v_mov_b32_dpp v151, v244 row_ror:1 row_mask:0xf bank_mask:0xf
	v_cndmask_b32_e64 v245, v95, v99, s[40:41]
	v_cndmask_b32_e64 v0, v91, v103, s[42:43]
	v_lshl_add_u64 v[106:107], s[16:17], 0, v[188:189]
	v_mov_b32_dpp v153, v245 row_ror:2 row_mask:0xf bank_mask:0xf
	v_mov_b32_dpp v109, v0 row_ror:1 row_mask:0xf bank_mask:0xf
	v_cndmask_b32_e64 v244, v91, v103, s[40:41]
	v_cndmask_b32_e64 v245, v96, v100, s[42:43]
	v_cndmask_b32_e64 v0, v96, v100, s[40:41]
	v_mov_b32_dpp v149, v244 row_ror:2 row_mask:0xf bank_mask:0xf
	v_mov_b32_dpp v102, v245 row_ror:1 row_mask:0xf bank_mask:0xf
	v_mov_b32_dpp v110, v0 row_ror:2 row_mask:0xf bank_mask:0xf
	v_cndmask_b32_e64 v244, v92, v104, s[42:43]
	v_cndmask_b32_e64 v245, v92, v104, s[40:41]
	v_cndmask_b32_e64 v0, v97, v101, s[42:43]
	v_mov_b32_dpp v98, v244 row_ror:1 row_mask:0xf bank_mask:0xf
	v_mov_b32_dpp v100, v245 row_ror:2 row_mask:0xf bank_mask:0xf
	v_mov_b32_dpp v103, v0 row_ror:1 row_mask:0xf bank_mask:0xf
	v_cndmask_b32_e64 v244, v97, v101, s[40:41]
	v_cndmask_b32_e64 v245, v93, v105, s[42:43]
	v_cndmask_b32_e64 v0, v93, v105, s[40:41]
	v_mov_b32_dpp v111, v244 row_ror:2 row_mask:0xf bank_mask:0xf
	v_mov_b32_dpp v99, v245 row_ror:1 row_mask:0xf bank_mask:0xf
	v_mov_b32_dpp v101, v0 row_ror:2 row_mask:0xf bank_mask:0xf
	s_and_saveexec_b64 s[18:19], s[46:47]
	s_cbranch_execz .LBB0_704
	s_waitcnt vmcnt(4)
	v_pk_fma_f32 v[104:105], v[130:131], v[152:153], v[142:143]
	v_pk_fma_f32 v[110:111], v[132:133], v[110:111], v[144:145]
	v_pk_fma_f32 v[104:105], v[134:135], v[150:151], v[104:105]
	v_pk_fma_f32 v[102:103], v[136:137], v[102:103], v[110:111]
	v_pk_fma_f32 v[104:105], v[94:95], v[138:139], v[104:105]
	v_pk_fma_f32 v[102:103], v[96:97], v[140:141], v[102:103]
	v_mul_f32_e32 v0, 0xbfb8aa3b, v104
	v_exp_f32_e32 v0, v0
	v_mul_f32_e32 v150, 0xbfb8aa3b, v105
	v_exp_f32_e32 v150, v150
	v_mul_f32_e32 v110, 0xbfb8aa3b, v103
	v_add_f32_e32 v0, 1.0, v0
	v_exp_f32_e32 v110, v110
	v_add_f32_e32 v151, 1.0, v150
	v_rcp_f32_e32 v150, v0
	v_mul_f32_e32 v0, 0xbfb8aa3b, v102
	v_rcp_f32_e32 v151, v151
	v_exp_f32_e32 v0, v0
	s_waitcnt vmcnt(6)
	v_pk_fma_f32 v[148:149], v[114:115], v[148:149], v[126:127]
	v_pk_fma_f32 v[100:101], v[116:117], v[100:101], v[128:129]
	v_pk_fma_f32 v[108:109], v[118:119], v[108:109], v[148:149]
	v_pk_mul_f32 v[104:105], v[104:105], v[150:151]
	v_pk_fma_f32 v[108:109], v[90:91], v[122:123], v[108:109]
	v_add_f32_e32 v0, 1.0, v0
	v_pk_mul_f32 v[104:105], v[108:109], v[104:105]
	v_rcp_f32_e32 v108, v0
	v_add_f32_e32 v0, 1.0, v110
	v_rcp_f32_e32 v109, v0
	v_pk_fma_f32 v[98:99], v[120:121], v[98:99], v[100:101]
	v_pk_mul_f32 v[100:101], v[102:103], v[108:109]
	v_pk_fma_f32 v[98:99], v[92:93], v[124:125], v[98:99]
	s_nop 0
	v_pk_mul_f32 v[98:99], v[98:99], v[100:101]
	v_cvt_pk_bf16_f32 v100, v104, v105
	v_cvt_pk_bf16_f32 v101, v98, v99
	v_mov_b64_e32 v[98:99], s[12:13]
	v_mad_u64_u32 v[98:99], s[26:27], v106, s60, v[98:99]
	v_mad_i32_i24 v99, v107, s60, v99
	v_lshl_add_u64 v[98:99], v[202:203], 1, v[98:99]
	global_store_dwordx2 v[98:99], v[100:101], off
.LBB0_704:
	s_or_b64 exec, exec, s[18:19]
	v_cndmask_b32_e64 v0, v86, v94, s[42:43]
	v_cndmask_b32_e64 v244, v86, v94, s[40:41]
	v_cndmask_b32_e64 v245, v82, v90, s[42:43]
	v_mov_b32_dpp v102, v0 row_ror:1 row_mask:0xf bank_mask:0xf
	v_mov_b32_dpp v104, v244 row_ror:2 row_mask:0xf bank_mask:0xf
	v_mov_b32_dpp v98, v245 row_ror:1 row_mask:0xf bank_mask:0xf
	v_cndmask_b32_e64 v0, v82, v90, s[40:41]
	v_cndmask_b32_e64 v244, v87, v95, s[42:43]
	v_lshl_add_u64 v[108:109], s[16:17], 0, v[190:191]
	v_mov_b32_dpp v100, v0 row_ror:2 row_mask:0xf bank_mask:0xf
	v_mov_b32_dpp v103, v244 row_ror:1 row_mask:0xf bank_mask:0xf
	v_cndmask_b32_e64 v245, v87, v95, s[40:41]
	v_cndmask_b32_e64 v0, v83, v91, s[42:43]
	v_cndmask_b32_e64 v244, v83, v91, s[40:41]
	v_mov_b32_dpp v105, v245 row_ror:2 row_mask:0xf bank_mask:0xf
	v_mov_b32_dpp v99, v0 row_ror:1 row_mask:0xf bank_mask:0xf
	v_mov_b32_dpp v101, v244 row_ror:2 row_mask:0xf bank_mask:0xf
	v_cndmask_b32_e64 v245, v88, v96, s[42:43]
	v_cndmask_b32_e64 v0, v88, v96, s[40:41]
	v_cndmask_b32_e64 v244, v84, v92, s[42:43]
	v_mov_b32_dpp v94, v245 row_ror:1 row_mask:0xf bank_mask:0xf
	v_mov_b32_dpp v96, v0 row_ror:2 row_mask:0xf bank_mask:0xf
	v_mov_b32_dpp v90, v244 row_ror:1 row_mask:0xf bank_mask:0xf
	v_cndmask_b32_e64 v245, v84, v92, s[40:41]
	v_cndmask_b32_e64 v0, v89, v97, s[42:43]
	v_cndmask_b32_e64 v244, v89, v97, s[40:41]
	v_mov_b32_dpp v92, v245 row_ror:2 row_mask:0xf bank_mask:0xf
	v_mov_b32_dpp v95, v0 row_ror:1 row_mask:0xf bank_mask:0xf
	v_mov_b32_dpp v97, v244 row_ror:2 row_mask:0xf bank_mask:0xf
	v_cndmask_b32_e64 v245, v85, v93, s[42:43]
	v_cndmask_b32_e64 v0, v85, v93, s[40:41]
	s_nop 0
	v_mov_b32_dpp v91, v245 row_ror:1 row_mask:0xf bank_mask:0xf
	v_mov_b32_dpp v93, v0 row_ror:2 row_mask:0xf bank_mask:0xf
	s_and_saveexec_b64 s[18:19], s[48:49]
	s_cbranch_execz .LBB0_706
; __device__ __forceinline__ unsigned cvt_pk_bf16(float lo, float hi) { const f32x2_t v = {lo, hi}; const bf16x2_t b = __builtin_convertvector(v, bf16x2_t); return __builtin_bit_cast(unsigned, b); }
; template <int N> __device__ __forceinline__ float dpp_ror(float v) { return __builtin_bit_cast(float, __builtin_amdgcn_update_dpp(0, __builtin_bit_cast(int, v), 0x120 + N, 0xf, 0xf, false)); }
;     __device__ __forceinline__ void operator()(const Acc& acc, const Unit& u, int wr, int wc, int fr, int fq) const {
;     ...
;                 for (int m = 0; m < 4; ++m) {
;                     const int rt = ai * 128 + wr * 64 + m * 16 + fr;
;                     const f32x4 g = acc[ai][0][m][n], up = acc[ai][1][m][n];
;                     const f32x4 gp = (m == 0) ? hg : acc[ai][0][m == 0 ? 0 : m - 1][n], upp = (m == 0) ? hu : acc[ai][1][m == 0 ? 0 : m - 1][n];
;                     f32x4 g1, g2, u1, u2;
; #pragma unroll
;                     for (int j = 0; j < 4; ++j) {
;                         g1[j] = dpp_ror<1>((fr == 15) ? gp[j] : g[j]); g2[j] = dpp_ror<2>((fr >= 14) ? gp[j] : g[j]);
;                         u1[j] = dpp_ror<1>((fr == 15) ? upp[j] : up[j]); u2[j] = dpp_ror<2>((fr >= 14) ? upp[j] : up[j]);
;                     }
;                     const f32x4 hcg = gb + gw0 * g2 + gw1 * g1 + gw2 * g, hcu = ub + uw0 * u2 + uw1 * u1 + uw2 * up;
;                     f32x4 a;
; #pragma unroll
;                     for (int j = 0; j < 4; ++j) a[j] = hcg[j] * __builtin_amdgcn_rcpf(1.f + __builtin_amdgcn_exp2f(-1.4426950408889634f * hcg[j])) * hcu[j];
;                     if (rt >= 2) { u32x2 w; w.x = cvt_pk_bf16(a[0], a[1]); w.y = cvt_pk_bf16(a[2], a[3]); *(u32x2*)(act + ((size_t)u.pm * 256 + rt) * DFF + ch) = w; }
	s_waitcnt vmcnt(4)
	v_pk_fma_f32 v[104:105], v[130:131], v[104:105], v[142:143]
	v_pk_fma_f32 v[96:97], v[132:133], v[96:97], v[144:145]
	v_pk_fma_f32 v[102:103], v[134:135], v[102:103], v[104:105]
	v_pk_fma_f32 v[94:95], v[136:137], v[94:95], v[96:97]
	v_pk_fma_f32 v[102:103], v[86:87], v[138:139], v[102:103]
	v_pk_fma_f32 v[94:95], v[88:89], v[140:141], v[94:95]
	v_mul_f32_e32 v0, 0xbfb8aa3b, v102
	v_mul_f32_e32 v104, 0xbfb8aa3b, v103
	v_exp_f32_e32 v0, v0
	v_exp_f32_e32 v104, v104
	s_waitcnt vmcnt(6)
	v_pk_fma_f32 v[100:101], v[114:115], v[100:101], v[126:127]
	v_mul_f32_e32 v96, 0xbfb8aa3b, v95
	v_add_f32_e32 v0, 1.0, v0
	v_add_f32_e32 v105, 1.0, v104
	v_rcp_f32_e32 v104, v0
	v_rcp_f32_e32 v105, v105
	v_mul_f32_e32 v0, 0xbfb8aa3b, v94
	v_exp_f32_e32 v0, v0
	v_pk_fma_f32 v[98:99], v[118:119], v[98:99], v[100:101]
	v_pk_mul_f32 v[100:101], v[102:103], v[104:105]
	v_exp_f32_e32 v102, v96
	v_pk_fma_f32 v[98:99], v[82:83], v[122:123], v[98:99]
	v_add_f32_e32 v0, 1.0, v0
	v_pk_mul_f32 v[96:97], v[98:99], v[100:101]
	v_rcp_f32_e32 v98, v0
	v_add_f32_e32 v0, 1.0, v102
	v_rcp_f32_e32 v99, v0
	v_pk_fma_f32 v[92:93], v[116:117], v[92:93], v[128:129]
	s_nop 0
	v_pk_fma_f32 v[90:91], v[120:121], v[90:91], v[92:93]
	v_pk_mul_f32 v[92:93], v[94:95], v[98:99]
	v_pk_fma_f32 v[90:91], v[84:85], v[124:125], v[90:91]
	s_nop 0
	v_pk_mul_f32 v[90:91], v[90:91], v[92:93]
	v_cvt_pk_bf16_f32 v92, v96, v97
	v_cvt_pk_bf16_f32 v93, v90, v91
	v_mov_b64_e32 v[90:91], s[12:13]
	v_mad_u64_u32 v[90:91], s[26:27], v108, s60, v[90:91]
	v_mad_i32_i24 v91, v109, s60, v91
	v_lshl_add_u64 v[90:91], v[202:203], 1, v[90:91]
	global_store_dwordx2 v[90:91], v[92:93], off
.LBB0_706:
	s_or_b64 exec, exec, s[18:19]
	v_cndmask_b32_e64 v0, v78, v86, s[42:43]
	v_cndmask_b32_e64 v244, v78, v86, s[40:41]
	v_cndmask_b32_e64 v245, v74, v82, s[42:43]
	v_mov_b32_dpp v94, v0 row_ror:1 row_mask:0xf bank_mask:0xf
	v_mov_b32_dpp v96, v244 row_ror:2 row_mask:0xf bank_mask:0xf
	v_mov_b32_dpp v90, v245 row_ror:1 row_mask:0xf bank_mask:0xf
	v_cndmask_b32_e64 v0, v74, v82, s[40:41]
	v_cndmask_b32_e64 v244, v79, v87, s[42:43]
	v_lshl_add_u64 v[110:111], s[16:17], 0, v[192:193]
	v_mov_b32_dpp v92, v0 row_ror:2 row_mask:0xf bank_mask:0xf
	v_mov_b32_dpp v95, v244 row_ror:1 row_mask:0xf bank_mask:0xf
	v_cndmask_b32_e64 v245, v79, v87, s[40:41]
	v_cndmask_b32_e64 v0, v75, v83, s[42:43]
	v_cndmask_b32_e64 v244, v75, v83, s[40:41]
	v_mov_b32_dpp v97, v245 row_ror:2 row_mask:0xf bank_mask:0xf
	v_mov_b32_dpp v91, v0 row_ror:1 row_mask:0xf bank_mask:0xf
	v_mov_b32_dpp v93, v244 row_ror:2 row_mask:0xf bank_mask:0xf
	v_cndmask_b32_e64 v245, v80, v88, s[42:43]
	v_cndmask_b32_e64 v0, v80, v88, s[40:41]
	v_cndmask_b32_e64 v244, v76, v84, s[42:43]
	v_mov_b32_dpp v86, v245 row_ror:1 row_mask:0xf bank_mask:0xf
	v_mov_b32_dpp v88, v0 row_ror:2 row_mask:0xf bank_mask:0xf
	v_mov_b32_dpp v82, v244 row_ror:1 row_mask:0xf bank_mask:0xf
	v_cndmask_b32_e64 v245, v76, v84, s[40:41]
	v_cndmask_b32_e64 v0, v81, v89, s[42:43]
	v_cndmask_b32_e64 v244, v81, v89, s[40:41]
	v_mov_b32_dpp v84, v245 row_ror:2 row_mask:0xf bank_mask:0xf
	v_mov_b32_dpp v87, v0 row_ror:1 row_mask:0xf bank_mask:0xf
	v_mov_b32_dpp v89, v244 row_ror:2 row_mask:0xf bank_mask:0xf
	v_cndmask_b32_e64 v245, v77, v85, s[42:43]
	v_cndmask_b32_e64 v0, v77, v85, s[40:41]
	s_nop 0
	v_mov_b32_dpp v83, v245 row_ror:1 row_mask:0xf bank_mask:0xf
	v_mov_b32_dpp v85, v0 row_ror:2 row_mask:0xf bank_mask:0xf
	s_and_saveexec_b64 s[18:19], s[50:51]
	s_cbranch_execz .LBB0_708
	s_waitcnt vmcnt(4)
	v_pk_fma_f32 v[96:97], v[130:131], v[96:97], v[142:143]
	v_pk_fma_f32 v[88:89], v[132:133], v[88:89], v[144:145]
	v_pk_fma_f32 v[94:95], v[134:135], v[94:95], v[96:97]
	v_pk_fma_f32 v[86:87], v[136:137], v[86:87], v[88:89]
	v_pk_fma_f32 v[94:95], v[78:79], v[138:139], v[94:95]
	v_pk_fma_f32 v[86:87], v[80:81], v[140:141], v[86:87]
	v_mul_f32_e32 v0, 0xbfb8aa3b, v94
	v_mul_f32_e32 v96, 0xbfb8aa3b, v95
	v_exp_f32_e32 v0, v0
	v_exp_f32_e32 v96, v96
	s_waitcnt vmcnt(6)
	v_pk_fma_f32 v[92:93], v[114:115], v[92:93], v[126:127]
	v_mul_f32_e32 v88, 0xbfb8aa3b, v87
	v_add_f32_e32 v0, 1.0, v0
	v_add_f32_e32 v97, 1.0, v96
	v_rcp_f32_e32 v96, v0
	v_rcp_f32_e32 v97, v97
	v_mul_f32_e32 v0, 0xbfb8aa3b, v86
	v_exp_f32_e32 v0, v0
	v_pk_fma_f32 v[90:91], v[118:119], v[90:91], v[92:93]
	v_pk_mul_f32 v[92:93], v[94:95], v[96:97]
	v_exp_f32_e32 v94, v88
	v_pk_fma_f32 v[90:91], v[74:75], v[122:123], v[90:91]
	v_add_f32_e32 v0, 1.0, v0
	v_pk_mul_f32 v[88:89], v[90:91], v[92:93]
	v_rcp_f32_e32 v90, v0
	v_add_f32_e32 v0, 1.0, v94
	v_rcp_f32_e32 v91, v0
	v_pk_fma_f32 v[84:85], v[116:117], v[84:85], v[128:129]
	s_nop 0
	v_pk_fma_f32 v[82:83], v[120:121], v[82:83], v[84:85]
	v_pk_mul_f32 v[84:85], v[86:87], v[90:91]
	v_pk_fma_f32 v[82:83], v[76:77], v[124:125], v[82:83]
	s_nop 0
	v_pk_mul_f32 v[82:83], v[82:83], v[84:85]
	v_cvt_pk_bf16_f32 v84, v88, v89
	v_cvt_pk_bf16_f32 v85, v82, v83
	v_mov_b64_e32 v[82:83], s[12:13]
	v_mad_u64_u32 v[82:83], s[26:27], v110, s60, v[82:83]
	v_mad_i32_i24 v83, v111, s60, v83
	v_lshl_add_u64 v[82:83], v[202:203], 1, v[82:83]
	global_store_dwordx2 v[82:83], v[84:85], off
; __device__ __forceinline__ unsigned cvt_pk_bf16(float lo, float hi) { const f32x2_t v = {lo, hi}; const bf16x2_t b = __builtin_convertvector(v, bf16x2_t); return __builtin_bit_cast(unsigned, b); }
; template <int N> __device__ __forceinline__ float dpp_ror(float v) { return __builtin_bit_cast(float, __builtin_amdgcn_update_dpp(0, __builtin_bit_cast(int, v), 0x120 + N, 0xf, 0xf, false)); }
;     __device__ __forceinline__ void operator()(const Acc& acc, const Unit& u, int wr, int wc, int fr, int fq) const {
;     ...
;                 for (int m = 0; m < 4; ++m) {
;                     const int rt = ai * 128 + wr * 64 + m * 16 + fr;
;                     const f32x4 g = acc[ai][0][m][n], up = acc[ai][1][m][n];
;                     const f32x4 gp = (m == 0) ? hg : acc[ai][0][m == 0 ? 0 : m - 1][n], upp = (m == 0) ? hu : acc[ai][1][m == 0 ? 0 : m - 1][n];
;                     f32x4 g1, g2, u1, u2;
; #pragma unroll
;                     for (int j = 0; j < 4; ++j) {
;                         g1[j] = dpp_ror<1>((fr == 15) ? gp[j] : g[j]); g2[j] = dpp_ror<2>((fr >= 14) ? gp[j] : g[j]);
;                         u1[j] = dpp_ror<1>((fr == 15) ? upp[j] : up[j]); u2[j] = dpp_ror<2>((fr >= 14) ? upp[j] : up[j]);
;                     }
;                     const f32x4 hcg = gb + gw0 * g2 + gw1 * g1 + gw2 * g, hcu = ub + uw0 * u2 + uw1 * u1 + uw2 * up;
;                     f32x4 a;
; #pragma unroll
;                     for (int j = 0; j < 4; ++j) a[j] = hcg[j] * __builtin_amdgcn_rcpf(1.f + __builtin_amdgcn_exp2f(-1.4426950408889634f * hcg[j])) * hcu[j];
;                     if (rt >= 2) { u32x2 w; w.x = cvt_pk_bf16(a[0], a[1]); w.y = cvt_pk_bf16(a[2], a[3]); *(u32x2*)(act + ((size_t)u.pm * 256 + rt) * DFF + ch) = w; }
.LBB0_708:
	s_or_b64 exec, exec, s[18:19]
	v_cndmask_b32_e64 v0, v70, v78, s[42:43]
	v_cndmask_b32_e64 v244, v70, v78, s[40:41]
	v_cndmask_b32_e64 v245, v66, v74, s[42:43]
	v_mov_b32_dpp v86, v0 row_ror:1 row_mask:0xf bank_mask:0xf
	v_mov_b32_dpp v88, v244 row_ror:2 row_mask:0xf bank_mask:0xf
	v_mov_b32_dpp v82, v245 row_ror:1 row_mask:0xf bank_mask:0xf
	v_cndmask_b32_e64 v0, v66, v74, s[40:41]
	v_cndmask_b32_e64 v244, v71, v79, s[42:43]
	v_lshl_add_u64 v[148:149], s[16:17], 0, v[194:195]
	v_mov_b32_dpp v84, v0 row_ror:2 row_mask:0xf bank_mask:0xf
	v_mov_b32_dpp v87, v244 row_ror:1 row_mask:0xf bank_mask:0xf
	v_cndmask_b32_e64 v245, v71, v79, s[40:41]
	v_cndmask_b32_e64 v0, v67, v75, s[42:43]
	v_cndmask_b32_e64 v244, v67, v75, s[40:41]
	v_mov_b32_dpp v89, v245 row_ror:2 row_mask:0xf bank_mask:0xf
	v_mov_b32_dpp v83, v0 row_ror:1 row_mask:0xf bank_mask:0xf
	v_mov_b32_dpp v85, v244 row_ror:2 row_mask:0xf bank_mask:0xf
	v_cndmask_b32_e64 v245, v72, v80, s[42:43]
	v_cndmask_b32_e64 v0, v72, v80, s[40:41]
	v_cndmask_b32_e64 v244, v68, v76, s[42:43]
	v_mov_b32_dpp v78, v245 row_ror:1 row_mask:0xf bank_mask:0xf
	v_mov_b32_dpp v80, v0 row_ror:2 row_mask:0xf bank_mask:0xf
	v_mov_b32_dpp v74, v244 row_ror:1 row_mask:0xf bank_mask:0xf
	v_cndmask_b32_e64 v245, v68, v76, s[40:41]
	v_cndmask_b32_e64 v0, v73, v81, s[42:43]
	v_cndmask_b32_e64 v244, v73, v81, s[40:41]
	v_mov_b32_dpp v76, v245 row_ror:2 row_mask:0xf bank_mask:0xf
	v_mov_b32_dpp v79, v0 row_ror:1 row_mask:0xf bank_mask:0xf
	v_mov_b32_dpp v81, v244 row_ror:2 row_mask:0xf bank_mask:0xf
	v_cndmask_b32_e64 v245, v69, v77, s[42:43]
	v_cndmask_b32_e64 v0, v69, v77, s[40:41]
	s_nop 0
	v_mov_b32_dpp v75, v245 row_ror:1 row_mask:0xf bank_mask:0xf
	v_mov_b32_dpp v77, v0 row_ror:2 row_mask:0xf bank_mask:0xf
	s_and_saveexec_b64 s[16:17], s[52:53]
	s_cbranch_execz .LBB0_710
	s_waitcnt vmcnt(4)
	v_pk_fma_f32 v[88:89], v[130:131], v[88:89], v[142:143]
	v_pk_fma_f32 v[80:81], v[132:133], v[80:81], v[144:145]
	v_pk_fma_f32 v[86:87], v[134:135], v[86:87], v[88:89]
	v_pk_fma_f32 v[78:79], v[136:137], v[78:79], v[80:81]
	v_pk_fma_f32 v[70:71], v[70:71], v[138:139], v[86:87]
	v_pk_fma_f32 v[72:73], v[72:73], v[140:141], v[78:79]
	v_mul_f32_e32 v0, 0xbfb8aa3b, v70
	v_exp_f32_e32 v0, v0
	v_mul_f32_e32 v86, 0xbfb8aa3b, v71
	v_exp_f32_e32 v86, v86
	v_mul_f32_e32 v78, 0xbfb8aa3b, v73
	v_add_f32_e32 v0, 1.0, v0
	v_exp_f32_e32 v78, v78
	v_add_f32_e32 v87, 1.0, v86
	v_rcp_f32_e32 v86, v0
	v_mul_f32_e32 v0, 0xbfb8aa3b, v72
	v_rcp_f32_e32 v87, v87
	v_exp_f32_e32 v0, v0
	s_waitcnt vmcnt(6)
	v_pk_fma_f32 v[84:85], v[114:115], v[84:85], v[126:127]
	v_pk_fma_f32 v[76:77], v[116:117], v[76:77], v[128:129]
	v_pk_fma_f32 v[82:83], v[118:119], v[82:83], v[84:85]
	v_pk_mul_f32 v[70:71], v[70:71], v[86:87]
	v_pk_fma_f32 v[66:67], v[66:67], v[122:123], v[82:83]
	v_add_f32_e32 v0, 1.0, v0
	v_pk_mul_f32 v[66:67], v[66:67], v[70:71]
	v_rcp_f32_e32 v70, v0
	v_add_f32_e32 v0, 1.0, v78
	v_rcp_f32_e32 v71, v0
	v_pk_fma_f32 v[74:75], v[120:121], v[74:75], v[76:77]
	v_cvt_pk_bf16_f32 v66, v66, v67
	v_pk_fma_f32 v[68:69], v[68:69], v[124:125], v[74:75]
	v_pk_mul_f32 v[70:71], v[72:73], v[70:71]
	s_nop 0
	v_pk_mul_f32 v[68:69], v[68:69], v[70:71]
	s_nop 0
	v_cvt_pk_bf16_f32 v67, v68, v69
	v_mov_b64_e32 v[68:69], s[12:13]
	v_mad_u64_u32 v[68:69], s[18:19], v148, s60, v[68:69]
	v_mad_i32_i24 v69, v149, s60, v69
	v_lshl_add_u64 v[68:69], v[202:203], 1, v[68:69]
	global_store_dwordx2 v[68:69], v[66:67], off

; __device__ __forceinline__ unsigned cvt_pk_bf16(float lo, float hi) { const f32x2_t v = {lo, hi}; const bf16x2_t b = __builtin_convertvector(v, bf16x2_t); return __builtin_bit_cast(unsigned, b); }
; template <int N> __device__ __forceinline__ float dpp_ror(float v) { return __builtin_bit_cast(float, __builtin_amdgcn_update_dpp(0, __builtin_bit_cast(int, v), 0x120 + N, 0xf, 0xf, false)); }
;     __device__ __forceinline__ void operator()(const Acc& acc, const Unit& u, int wr, int wc, int fr, int fq) const {
;     ...
;                 for (int m = 0; m < 4; ++m) {
;                     const int rt = ai * 128 + wr * 64 + m * 16 + fr;
;                     const f32x4 g = acc[ai][0][m][n], up = acc[ai][1][m][n];
;                     const f32x4 gp = (m == 0) ? hg : acc[ai][0][m == 0 ? 0 : m - 1][n], upp = (m == 0) ? hu : acc[ai][1][m == 0 ? 0 : m - 1][n];
;                     f32x4 g1, g2, u1, u2;
; #pragma unroll
;                     for (int j = 0; j < 4; ++j) {
;                         g1[j] = dpp_ror<1>((fr == 15) ? gp[j] : g[j]); g2[j] = dpp_ror<2>((fr >= 14) ? gp[j] : g[j]);
;                         u1[j] = dpp_ror<1>((fr == 15) ? upp[j] : up[j]); u2[j] = dpp_ror<2>((fr >= 14) ? upp[j] : up[j]);
;                     }
;                     const f32x4 hcg = gb + gw0 * g2 + gw1 * g1 + gw2 * g, hcu = ub + uw0 * u2 + uw1 * u1 + uw2 * up;
;                     f32x4 a;
; #pragma unroll
;                     for (int j = 0; j < 4; ++j) a[j] = hcg[j] * __builtin_amdgcn_rcpf(1.f + __builtin_amdgcn_exp2f(-1.4426950408889634f * hcg[j])) * hcu[j];
;                     if (rt >= 2) { u32x2 w; w.x = cvt_pk_bf16(a[0], a[1]); w.y = cvt_pk_bf16(a[2], a[3]); *(u32x2*)(act + ((size_t)u.pm * 256 + rt) * DFF + ch) = w; }
.LBB0_714:
	s_or_b64 exec, exec, s[16:17]
	v_cndmask_b32_e64 v0, v54, v62, s[42:43]
	v_cndmask_b32_e64 v244, v54, v62, s[40:41]
	v_cndmask_b32_e64 v245, v50, v58, s[42:43]
	v_mov_b32_dpp v102, v0 row_ror:1 row_mask:0xf bank_mask:0xf
	v_mov_b32_dpp v104, v244 row_ror:2 row_mask:0xf bank_mask:0xf
	v_mov_b32_dpp v98, v245 row_ror:1 row_mask:0xf bank_mask:0xf
	v_cndmask_b32_e64 v0, v50, v58, s[40:41]
	v_cndmask_b32_e64 v244, v55, v63, s[42:43]
	s_and_b64 vcc, exec, s[56:57]
	v_mov_b32_dpp v100, v0 row_ror:2 row_mask:0xf bank_mask:0xf
	v_mov_b32_dpp v103, v244 row_ror:1 row_mask:0xf bank_mask:0xf
	v_cndmask_b32_e64 v245, v55, v63, s[40:41]
	v_cndmask_b32_e64 v0, v51, v59, s[42:43]
	v_cndmask_b32_e64 v244, v51, v59, s[40:41]
	v_mov_b32_dpp v105, v245 row_ror:2 row_mask:0xf bank_mask:0xf
	v_mov_b32_dpp v99, v0 row_ror:1 row_mask:0xf bank_mask:0xf
	v_mov_b32_dpp v101, v244 row_ror:2 row_mask:0xf bank_mask:0xf
	v_cndmask_b32_e64 v245, v56, v64, s[42:43]
	v_cndmask_b32_e64 v0, v56, v64, s[40:41]
	v_cndmask_b32_e64 v244, v52, v60, s[42:43]
	v_mov_b32_dpp v62, v245 row_ror:1 row_mask:0xf bank_mask:0xf
	v_mov_b32_dpp v64, v0 row_ror:2 row_mask:0xf bank_mask:0xf
	v_mov_b32_dpp v58, v244 row_ror:1 row_mask:0xf bank_mask:0xf
	v_cndmask_b32_e64 v245, v52, v60, s[40:41]
	v_cndmask_b32_e64 v0, v57, v65, s[42:43]
	v_cndmask_b32_e64 v244, v57, v65, s[40:41]
	v_mov_b32_dpp v60, v245 row_ror:2 row_mask:0xf bank_mask:0xf
	v_mov_b32_dpp v63, v0 row_ror:1 row_mask:0xf bank_mask:0xf
	v_mov_b32_dpp v65, v244 row_ror:2 row_mask:0xf bank_mask:0xf
	v_cndmask_b32_e64 v245, v53, v61, s[42:43]
	v_cndmask_b32_e64 v0, v53, v61, s[40:41]
	s_nop 0
	v_mov_b32_dpp v59, v245 row_ror:1 row_mask:0xf bank_mask:0xf
	v_mov_b32_dpp v61, v0 row_ror:2 row_mask:0xf bank_mask:0xf
	s_cbranch_vccnz .LBB0_716
	s_waitcnt vmcnt(4)
	v_pk_fma_f32 v[104:105], v[82:83], v[104:105], v[94:95]
	v_pk_fma_f32 v[64:65], v[84:85], v[64:65], v[96:97]
	v_pk_fma_f32 v[102:103], v[86:87], v[102:103], v[104:105]
	v_pk_fma_f32 v[62:63], v[88:89], v[62:63], v[64:65]
	v_pk_fma_f32 v[102:103], v[54:55], v[90:91], v[102:103]
	v_pk_fma_f32 v[62:63], v[56:57], v[92:93], v[62:63]
	v_mul_f32_e32 v0, 0xbfb8aa3b, v102
	v_mul_f32_e32 v104, 0xbfb8aa3b, v103
	v_exp_f32_e32 v0, v0
	v_exp_f32_e32 v104, v104
	s_waitcnt vmcnt(6)
	v_pk_fma_f32 v[100:101], v[66:67], v[100:101], v[78:79]
	v_mul_f32_e32 v64, 0xbfb8aa3b, v63
	v_add_f32_e32 v0, 1.0, v0
	v_add_f32_e32 v105, 1.0, v104
	v_rcp_f32_e32 v104, v0
	v_rcp_f32_e32 v105, v105
	v_mul_f32_e32 v0, 0xbfb8aa3b, v62
	v_exp_f32_e32 v0, v0
	v_pk_fma_f32 v[98:99], v[70:71], v[98:99], v[100:101]
	v_pk_mul_f32 v[100:101], v[102:103], v[104:105]
	v_exp_f32_e32 v102, v64
	v_pk_fma_f32 v[98:99], v[50:51], v[74:75], v[98:99]
	v_add_f32_e32 v0, 1.0, v0
	v_pk_mul_f32 v[64:65], v[98:99], v[100:101]
	v_rcp_f32_e32 v98, v0
	v_add_f32_e32 v0, 1.0, v102
	v_rcp_f32_e32 v99, v0
	v_pk_fma_f32 v[60:61], v[68:69], v[60:61], v[80:81]
	s_nop 0
	v_pk_fma_f32 v[58:59], v[72:73], v[58:59], v[60:61]
	v_pk_mul_f32 v[60:61], v[62:63], v[98:99]
	v_pk_fma_f32 v[58:59], v[52:53], v[76:77], v[58:59]
	s_nop 0
	v_pk_mul_f32 v[58:59], v[58:59], v[60:61]
	v_cvt_pk_bf16_f32 v60, v64, v65
	v_cvt_pk_bf16_f32 v61, v58, v59
	v_mov_b64_e32 v[58:59], s[12:13]
	v_mad_u64_u32 v[58:59], s[16:17], v154, s60, v[58:59]
	v_mad_i32_i24 v59, v155, s60, v59
	v_lshl_add_u64 v[58:59], v[202:203], 1, v[58:59]
	global_store_dwordx2 v[58:59], v[60:61], off offset:8
; __device__ __forceinline__ unsigned cvt_pk_bf16(float lo, float hi) { const f32x2_t v = {lo, hi}; const bf16x2_t b = __builtin_convertvector(v, bf16x2_t); return __builtin_bit_cast(unsigned, b); }
; template <int N> __device__ __forceinline__ float dpp_ror(float v) { return __builtin_bit_cast(float, __builtin_amdgcn_update_dpp(0, __builtin_bit_cast(int, v), 0x120 + N, 0xf, 0xf, false)); }
;     __device__ __forceinline__ void operator()(const Acc& acc, const Unit& u, int wr, int wc, int fr, int fq) const {
;     ...
;                 for (int m = 0; m < 4; ++m) {
;                     const int rt = ai * 128 + wr * 64 + m * 16 + fr;
;                     const f32x4 g = acc[ai][0][m][n], up = acc[ai][1][m][n];
;                     const f32x4 gp = (m == 0) ? hg : acc[ai][0][m == 0 ? 0 : m - 1][n], upp = (m == 0) ? hu : acc[ai][1][m == 0 ? 0 : m - 1][n];
;                     f32x4 g1, g2, u1, u2;
; #pragma unroll
;                     for (int j = 0; j < 4; ++j) {
;                         g1[j] = dpp_ror<1>((fr == 15) ? gp[j] : g[j]); g2[j] = dpp_ror<2>((fr >= 14) ? gp[j] : g[j]);
;                         u1[j] = dpp_ror<1>((fr == 15) ? upp[j] : up[j]); u2[j] = dpp_ror<2>((fr >= 14) ? upp[j] : up[j]);
;                     }
;                     const f32x4 hcg = gb + gw0 * g2 + gw1 * g1 + gw2 * g, hcu = ub + uw0 * u2 + uw1 * u1 + uw2 * up;
;                     f32x4 a;
; #pragma unroll
;                     for (int j = 0; j < 4; ++j) a[j] = hcg[j] * __builtin_amdgcn_rcpf(1.f + __builtin_amdgcn_exp2f(-1.4426950408889634f * hcg[j])) * hcu[j];
;                     if (rt >= 2) { u32x2 w; w.x = cvt_pk_bf16(a[0], a[1]); w.y = cvt_pk_bf16(a[2], a[3]); *(u32x2*)(act + ((size_t)u.pm * 256 + rt) * DFF + ch) = w; }
.LBB0_716:
	v_cndmask_b32_e64 v0, v46, v54, s[42:43]
	v_cndmask_b32_e64 v244, v46, v54, s[40:41]
	v_cndmask_b32_e64 v245, v42, v50, s[42:43]
	v_mov_b32_dpp v62, v0 row_ror:1 row_mask:0xf bank_mask:0xf
	v_mov_b32_dpp v64, v244 row_ror:2 row_mask:0xf bank_mask:0xf
	v_mov_b32_dpp v58, v245 row_ror:1 row_mask:0xf bank_mask:0xf
	v_cndmask_b32_e64 v0, v42, v50, s[40:41]
	v_cndmask_b32_e64 v244, v47, v55, s[42:43]
	s_and_b64 vcc, exec, s[56:57]
	v_mov_b32_dpp v60, v0 row_ror:2 row_mask:0xf bank_mask:0xf
	v_mov_b32_dpp v63, v244 row_ror:1 row_mask:0xf bank_mask:0xf
	v_cndmask_b32_e64 v245, v47, v55, s[40:41]
	v_cndmask_b32_e64 v0, v43, v51, s[42:43]
	v_cndmask_b32_e64 v244, v43, v51, s[40:41]
	v_mov_b32_dpp v65, v245 row_ror:2 row_mask:0xf bank_mask:0xf
	v_mov_b32_dpp v59, v0 row_ror:1 row_mask:0xf bank_mask:0xf
	v_mov_b32_dpp v61, v244 row_ror:2 row_mask:0xf bank_mask:0xf
	v_cndmask_b32_e64 v245, v48, v56, s[42:43]
	v_cndmask_b32_e64 v0, v48, v56, s[40:41]
	v_cndmask_b32_e64 v244, v44, v52, s[42:43]
	v_mov_b32_dpp v54, v245 row_ror:1 row_mask:0xf bank_mask:0xf
	v_mov_b32_dpp v56, v0 row_ror:2 row_mask:0xf bank_mask:0xf
	v_mov_b32_dpp v50, v244 row_ror:1 row_mask:0xf bank_mask:0xf
	v_cndmask_b32_e64 v245, v44, v52, s[40:41]
	v_cndmask_b32_e64 v0, v49, v57, s[42:43]
	v_cndmask_b32_e64 v244, v49, v57, s[40:41]
	v_mov_b32_dpp v52, v245 row_ror:2 row_mask:0xf bank_mask:0xf
	v_mov_b32_dpp v55, v0 row_ror:1 row_mask:0xf bank_mask:0xf
	v_mov_b32_dpp v57, v244 row_ror:2 row_mask:0xf bank_mask:0xf
	v_cndmask_b32_e64 v245, v45, v53, s[42:43]
	v_cndmask_b32_e64 v0, v45, v53, s[40:41]
	s_nop 0
	v_mov_b32_dpp v51, v245 row_ror:1 row_mask:0xf bank_mask:0xf
	v_mov_b32_dpp v53, v0 row_ror:2 row_mask:0xf bank_mask:0xf
	s_cbranch_vccnz .LBB0_718
	s_waitcnt vmcnt(4)
	v_pk_fma_f32 v[64:65], v[82:83], v[64:65], v[94:95]
	v_pk_fma_f32 v[56:57], v[84:85], v[56:57], v[96:97]
	v_pk_fma_f32 v[62:63], v[86:87], v[62:63], v[64:65]
	v_pk_fma_f32 v[54:55], v[88:89], v[54:55], v[56:57]
	v_pk_fma_f32 v[62:63], v[46:47], v[90:91], v[62:63]
	v_pk_fma_f32 v[54:55], v[48:49], v[92:93], v[54:55]
	v_mul_f32_e32 v0, 0xbfb8aa3b, v62
	v_mul_f32_e32 v64, 0xbfb8aa3b, v63
	v_exp_f32_e32 v0, v0
	v_exp_f32_e32 v64, v64
	s_waitcnt vmcnt(6)
	v_pk_fma_f32 v[60:61], v[66:67], v[60:61], v[78:79]
	v_mul_f32_e32 v56, 0xbfb8aa3b, v55
	v_add_f32_e32 v0, 1.0, v0
	v_add_f32_e32 v65, 1.0, v64
	v_rcp_f32_e32 v64, v0
	v_rcp_f32_e32 v65, v65
	v_mul_f32_e32 v0, 0xbfb8aa3b, v54
	v_exp_f32_e32 v0, v0
	v_pk_fma_f32 v[58:59], v[70:71], v[58:59], v[60:61]
	v_pk_mul_f32 v[60:61], v[62:63], v[64:65]
	v_exp_f32_e32 v62, v56
	v_pk_fma_f32 v[58:59], v[42:43], v[74:75], v[58:59]
	v_add_f32_e32 v0, 1.0, v0
	v_pk_mul_f32 v[56:57], v[58:59], v[60:61]
	v_rcp_f32_e32 v58, v0
	v_add_f32_e32 v0, 1.0, v62
	v_rcp_f32_e32 v59, v0
	v_pk_fma_f32 v[52:53], v[68:69], v[52:53], v[80:81]
	s_nop 0
	v_pk_fma_f32 v[50:51], v[72:73], v[50:51], v[52:53]
	v_pk_mul_f32 v[52:53], v[54:55], v[58:59]
	v_pk_fma_f32 v[50:51], v[44:45], v[76:77], v[50:51]
	s_nop 0
	v_pk_mul_f32 v[50:51], v[50:51], v[52:53]
	v_cvt_pk_bf16_f32 v52, v56, v57
	v_cvt_pk_bf16_f32 v53, v50, v51
	v_mov_b64_e32 v[50:51], s[12:13]
	v_mad_u64_u32 v[50:51], s[16:17], v146, s60, v[50:51]
	v_mad_i32_i24 v51, v147, s60, v51
	v_lshl_add_u64 v[50:51], v[202:203], 1, v[50:51]
	global_store_dwordx2 v[50:51], v[52:53], off offset:8
.LBB0_718:
	v_cndmask_b32_e64 v0, v38, v46, s[42:43]
	v_cndmask_b32_e64 v244, v38, v46, s[40:41]
	v_cndmask_b32_e64 v245, v34, v42, s[42:43]
	v_mov_b32_dpp v54, v0 row_ror:1 row_mask:0xf bank_mask:0xf
	v_mov_b32_dpp v56, v244 row_ror:2 row_mask:0xf bank_mask:0xf
	v_mov_b32_dpp v50, v245 row_ror:1 row_mask:0xf bank_mask:0xf
	v_cndmask_b32_e64 v0, v34, v42, s[40:41]
	v_cndmask_b32_e64 v244, v39, v47, s[42:43]
	s_and_b64 vcc, exec, s[56:57]
	v_mov_b32_dpp v52, v0 row_ror:2 row_mask:0xf bank_mask:0xf
	v_mov_b32_dpp v55, v244 row_ror:1 row_mask:0xf bank_mask:0xf
	v_cndmask_b32_e64 v245, v39, v47, s[40:41]
	v_cndmask_b32_e64 v0, v35, v43, s[42:43]
	v_cndmask_b32_e64 v244, v35, v43, s[40:41]
	v_mov_b32_dpp v57, v245 row_ror:2 row_mask:0xf bank_mask:0xf
	v_mov_b32_dpp v51, v0 row_ror:1 row_mask:0xf bank_mask:0xf
	v_mov_b32_dpp v53, v244 row_ror:2 row_mask:0xf bank_mask:0xf
	v_cndmask_b32_e64 v245, v40, v48, s[42:43]
	v_cndmask_b32_e64 v0, v40, v48, s[40:41]
	v_cndmask_b32_e64 v244, v36, v44, s[42:43]
	v_mov_b32_dpp v46, v245 row_ror:1 row_mask:0xf bank_mask:0xf
	v_mov_b32_dpp v48, v0 row_ror:2 row_mask:0xf bank_mask:0xf
	v_mov_b32_dpp v42, v244 row_ror:1 row_mask:0xf bank_mask:0xf
	v_cndmask_b32_e64 v245, v36, v44, s[40:41]
	v_cndmask_b32_e64 v0, v41, v49, s[42:43]
	v_cndmask_b32_e64 v244, v41, v49, s[40:41]
	v_mov_b32_dpp v44, v245 row_ror:2 row_mask:0xf bank_mask:0xf
	v_mov_b32_dpp v47, v0 row_ror:1 row_mask:0xf bank_mask:0xf
	v_mov_b32_dpp v49, v244 row_ror:2 row_mask:0xf bank_mask:0xf
	v_cndmask_b32_e64 v245, v37, v45, s[42:43]
	v_cndmask_b32_e64 v0, v37, v45, s[40:41]
	s_nop 0
	v_mov_b32_dpp v43, v245 row_ror:1 row_mask:0xf bank_mask:0xf
	v_mov_b32_dpp v45, v0 row_ror:2 row_mask:0xf bank_mask:0xf
	s_cbranch_vccnz .LBB0_720
	s_waitcnt vmcnt(4)
	v_pk_fma_f32 v[56:57], v[82:83], v[56:57], v[94:95]
	v_pk_fma_f32 v[48:49], v[84:85], v[48:49], v[96:97]
	v_pk_fma_f32 v[54:55], v[86:87], v[54:55], v[56:57]
	v_pk_fma_f32 v[46:47], v[88:89], v[46:47], v[48:49]
	v_pk_fma_f32 v[38:39], v[38:39], v[90:91], v[54:55]
	v_pk_fma_f32 v[40:41], v[40:41], v[92:93], v[46:47]
	v_mul_f32_e32 v0, 0xbfb8aa3b, v38
	v_exp_f32_e32 v0, v0
	v_mul_f32_e32 v54, 0xbfb8aa3b, v39
	v_exp_f32_e32 v54, v54
	v_mul_f32_e32 v46, 0xbfb8aa3b, v41
	v_add_f32_e32 v0, 1.0, v0
	v_exp_f32_e32 v46, v46
	v_add_f32_e32 v55, 1.0, v54
	v_rcp_f32_e32 v54, v0
	v_mul_f32_e32 v0, 0xbfb8aa3b, v40
	v_rcp_f32_e32 v55, v55
	v_exp_f32_e32 v0, v0
	s_waitcnt vmcnt(6)
	v_pk_fma_f32 v[52:53], v[66:67], v[52:53], v[78:79]
	v_pk_fma_f32 v[44:45], v[68:69], v[44:45], v[80:81]
	v_pk_fma_f32 v[50:51], v[70:71], v[50:51], v[52:53]
	v_pk_mul_f32 v[38:39], v[38:39], v[54:55]
	v_pk_fma_f32 v[34:35], v[34:35], v[74:75], v[50:51]
	v_add_f32_e32 v0, 1.0, v0
	v_pk_mul_f32 v[34:35], v[34:35], v[38:39]
	v_rcp_f32_e32 v38, v0
	v_add_f32_e32 v0, 1.0, v46
	v_rcp_f32_e32 v39, v0
	v_pk_fma_f32 v[42:43], v[72:73], v[42:43], v[44:45]
	v_cvt_pk_bf16_f32 v34, v34, v35
	v_pk_fma_f32 v[36:37], v[36:37], v[76:77], v[42:43]
	v_pk_mul_f32 v[38:39], v[40:41], v[38:39]
	s_nop 0
	v_pk_mul_f32 v[36:37], v[36:37], v[38:39]
	s_nop 0
	v_cvt_pk_bf16_f32 v35, v36, v37
	v_mov_b64_e32 v[36:37], s[12:13]
	v_mad_u64_u32 v[36:37], s[16:17], v112, s60, v[36:37]
	v_mad_i32_i24 v37, v113, s60, v37
	v_lshl_add_u64 v[36:37], v[202:203], 1, v[36:37]
	global_store_dwordx2 v[36:37], v[34:35], off offset:8

; __device__ __forceinline__ unsigned cvt_pk_bf16(float lo, float hi) { const f32x2_t v = {lo, hi}; const bf16x2_t b = __builtin_convertvector(v, bf16x2_t); return __builtin_bit_cast(unsigned, b); }
; template <int N> __device__ __forceinline__ float dpp_ror(float v) { return __builtin_bit_cast(float, __builtin_amdgcn_update_dpp(0, __builtin_bit_cast(int, v), 0x120 + N, 0xf, 0xf, false)); }
;     __device__ __forceinline__ void operator()(const Acc& acc, const Unit& u, int wr, int wc, int fr, int fq) const {
;     ...
;                 for (int m = 0; m < 4; ++m) {
;                     const int rt = ai * 128 + wr * 64 + m * 16 + fr;
;                     const f32x4 g = acc[ai][0][m][n], up = acc[ai][1][m][n];
;                     const f32x4 gp = (m == 0) ? hg : acc[ai][0][m == 0 ? 0 : m - 1][n], upp = (m == 0) ? hu : acc[ai][1][m == 0 ? 0 : m - 1][n];
;                     f32x4 g1, g2, u1, u2;
; #pragma unroll
;                     for (int j = 0; j < 4; ++j) {
;                         g1[j] = dpp_ror<1>((fr == 15) ? gp[j] : g[j]); g2[j] = dpp_ror<2>((fr >= 14) ? gp[j] : g[j]);
;                         u1[j] = dpp_ror<1>((fr == 15) ? upp[j] : up[j]); u2[j] = dpp_ror<2>((fr >= 14) ? upp[j] : up[j]);
;                     }
;                     const f32x4 hcg = gb + gw0 * g2 + gw1 * g1 + gw2 * g, hcu = ub + uw0 * u2 + uw1 * u1 + uw2 * up;
;                     f32x4 a;
; #pragma unroll
;                     for (int j = 0; j < 4; ++j) a[j] = hcg[j] * __builtin_amdgcn_rcpf(1.f + __builtin_amdgcn_exp2f(-1.4426950408889634f * hcg[j])) * hcu[j];
;                     if (rt >= 2) { u32x2 w; w.x = cvt_pk_bf16(a[0], a[1]); w.y = cvt_pk_bf16(a[2], a[3]); *(u32x2*)(act + ((size_t)u.pm * 256 + rt) * DFF + ch) = w; }
.LBB0_722:
	s_or_b64 exec, exec, s[16:17]
	s_waitcnt lgkmcnt(1)
	v_cndmask_b32_e64 v0, v30, v34, s[42:43]
	v_cndmask_b32_e64 v244, v30, v34, s[40:41]
	s_waitcnt lgkmcnt(0)
	v_mov_b32_dpp v48, v0 row_ror:1 row_mask:0xf bank_mask:0xf
	v_mov_b32_dpp v50, v244 row_ror:2 row_mask:0xf bank_mask:0xf
	v_cndmask_b32_e64 v245, v26, v38, s[42:43]
	v_cndmask_b32_e64 v0, v26, v38, s[40:41]
	v_cndmask_b32_e64 v244, v31, v35, s[42:43]
	v_mov_b32_dpp v42, v245 row_ror:1 row_mask:0xf bank_mask:0xf
	v_mov_b32_dpp v46, v0 row_ror:2 row_mask:0xf bank_mask:0xf
	v_mov_b32_dpp v49, v244 row_ror:1 row_mask:0xf bank_mask:0xf
	v_cndmask_b32_e64 v245, v31, v35, s[40:41]
	v_cndmask_b32_e64 v0, v27, v39, s[42:43]
	v_cndmask_b32_e64 v244, v27, v39, s[40:41]
	v_mov_b32_dpp v51, v245 row_ror:2 row_mask:0xf bank_mask:0xf
	v_mov_b32_dpp v43, v0 row_ror:1 row_mask:0xf bank_mask:0xf
	v_mov_b32_dpp v47, v244 row_ror:2 row_mask:0xf bank_mask:0xf
	v_cndmask_b32_e64 v245, v32, v36, s[42:43]
	v_cndmask_b32_e64 v0, v32, v36, s[40:41]
	v_cndmask_b32_e64 v244, v28, v40, s[42:43]
	v_mov_b32_dpp v38, v245 row_ror:1 row_mask:0xf bank_mask:0xf
	v_mov_b32_dpp v44, v0 row_ror:2 row_mask:0xf bank_mask:0xf
	v_mov_b32_dpp v34, v244 row_ror:1 row_mask:0xf bank_mask:0xf
	v_cndmask_b32_e64 v245, v28, v40, s[40:41]
	v_cndmask_b32_e64 v0, v33, v37, s[42:43]
	v_cndmask_b32_e64 v244, v33, v37, s[40:41]
	v_mov_b32_dpp v36, v245 row_ror:2 row_mask:0xf bank_mask:0xf
	v_mov_b32_dpp v39, v0 row_ror:1 row_mask:0xf bank_mask:0xf
	v_mov_b32_dpp v45, v244 row_ror:2 row_mask:0xf bank_mask:0xf
	v_cndmask_b32_e64 v245, v29, v41, s[42:43]
	v_cndmask_b32_e64 v0, v29, v41, s[40:41]
	s_nop 0
	v_mov_b32_dpp v35, v245 row_ror:1 row_mask:0xf bank_mask:0xf
	v_mov_b32_dpp v37, v0 row_ror:2 row_mask:0xf bank_mask:0xf
	s_and_saveexec_b64 s[16:17], s[46:47]
	s_cbranch_execz .LBB0_724
	s_waitcnt vmcnt(4)
	v_pk_fma_f32 v[40:41], v[82:83], v[50:51], v[94:95]
	v_pk_fma_f32 v[44:45], v[84:85], v[44:45], v[96:97]
	v_pk_fma_f32 v[40:41], v[86:87], v[48:49], v[40:41]
	v_pk_fma_f32 v[38:39], v[88:89], v[38:39], v[44:45]
	v_pk_fma_f32 v[40:41], v[30:31], v[90:91], v[40:41]
	v_pk_fma_f32 v[38:39], v[32:33], v[92:93], v[38:39]
	v_mul_f32_e32 v0, 0xbfb8aa3b, v40
	v_exp_f32_e32 v0, v0
	v_mul_f32_e32 v48, 0xbfb8aa3b, v41
	v_exp_f32_e32 v48, v48
	v_mul_f32_e32 v44, 0xbfb8aa3b, v39
	v_add_f32_e32 v0, 1.0, v0
	v_exp_f32_e32 v44, v44
	v_add_f32_e32 v49, 1.0, v48
	v_rcp_f32_e32 v48, v0
	v_mul_f32_e32 v0, 0xbfb8aa3b, v38
	v_rcp_f32_e32 v49, v49
	v_exp_f32_e32 v0, v0
	s_waitcnt vmcnt(6)
	v_pk_fma_f32 v[46:47], v[66:67], v[46:47], v[78:79]
	v_pk_fma_f32 v[36:37], v[68:69], v[36:37], v[80:81]
	v_pk_fma_f32 v[42:43], v[70:71], v[42:43], v[46:47]
	v_pk_mul_f32 v[40:41], v[40:41], v[48:49]
	v_pk_fma_f32 v[42:43], v[26:27], v[74:75], v[42:43]
	v_add_f32_e32 v0, 1.0, v0
	v_pk_mul_f32 v[40:41], v[42:43], v[40:41]
	v_rcp_f32_e32 v42, v0
	v_add_f32_e32 v0, 1.0, v44
	v_rcp_f32_e32 v43, v0
	v_pk_fma_f32 v[34:35], v[72:73], v[34:35], v[36:37]
	v_pk_mul_f32 v[36:37], v[38:39], v[42:43]
	v_pk_fma_f32 v[34:35], v[28:29], v[76:77], v[34:35]
	s_nop 0
	v_pk_mul_f32 v[34:35], v[34:35], v[36:37]
	v_cvt_pk_bf16_f32 v36, v40, v41
	v_cvt_pk_bf16_f32 v37, v34, v35
	v_mov_b64_e32 v[34:35], s[12:13]
	v_mad_u64_u32 v[34:35], s[18:19], v106, s60, v[34:35]
	v_mad_i32_i24 v35, v107, s60, v35
	v_lshl_add_u64 v[34:35], v[202:203], 1, v[34:35]
	global_store_dwordx2 v[34:35], v[36:37], off offset:8
.LBB0_724:
	s_or_b64 exec, exec, s[16:17]
	v_cndmask_b32_e64 v0, v22, v30, s[42:43]
	v_cndmask_b32_e64 v244, v22, v30, s[40:41]
	v_cndmask_b32_e64 v245, v18, v26, s[42:43]
	v_mov_b32_dpp v38, v0 row_ror:1 row_mask:0xf bank_mask:0xf
	v_mov_b32_dpp v40, v244 row_ror:2 row_mask:0xf bank_mask:0xf
	v_mov_b32_dpp v34, v245 row_ror:1 row_mask:0xf bank_mask:0xf
	v_cndmask_b32_e64 v0, v18, v26, s[40:41]
	v_cndmask_b32_e64 v244, v23, v31, s[42:43]
	v_cndmask_b32_e64 v245, v23, v31, s[40:41]
	v_mov_b32_dpp v36, v0 row_ror:2 row_mask:0xf bank_mask:0xf
	v_mov_b32_dpp v39, v244 row_ror:1 row_mask:0xf bank_mask:0xf
	v_mov_b32_dpp v41, v245 row_ror:2 row_mask:0xf bank_mask:0xf
	v_cndmask_b32_e64 v0, v19, v27, s[42:43]
	v_cndmask_b32_e64 v244, v19, v27, s[40:41]
	v_cndmask_b32_e64 v245, v24, v32, s[42:43]
	v_mov_b32_dpp v35, v0 row_ror:1 row_mask:0xf bank_mask:0xf
	v_mov_b32_dpp v37, v244 row_ror:2 row_mask:0xf bank_mask:0xf
	v_mov_b32_dpp v30, v245 row_ror:1 row_mask:0xf bank_mask:0xf
	v_cndmask_b32_e64 v0, v24, v32, s[40:41]
	v_cndmask_b32_e64 v244, v20, v28, s[42:43]
	v_cndmask_b32_e64 v245, v20, v28, s[40:41]
	v_mov_b32_dpp v32, v0 row_ror:2 row_mask:0xf bank_mask:0xf
	v_mov_b32_dpp v26, v244 row_ror:1 row_mask:0xf bank_mask:0xf
	v_mov_b32_dpp v28, v245 row_ror:2 row_mask:0xf bank_mask:0xf
	v_cndmask_b32_e64 v0, v25, v33, s[42:43]
	v_cndmask_b32_e64 v244, v25, v33, s[40:41]
	v_cndmask_b32_e64 v245, v21, v29, s[42:43]
	v_mov_b32_dpp v31, v0 row_ror:1 row_mask:0xf bank_mask:0xf
	v_mov_b32_dpp v33, v244 row_ror:2 row_mask:0xf bank_mask:0xf
	v_mov_b32_dpp v27, v245 row_ror:1 row_mask:0xf bank_mask:0xf
	v_cndmask_b32_e64 v0, v21, v29, s[40:41]
	s_nop 1
	v_mov_b32_dpp v29, v0 row_ror:2 row_mask:0xf bank_mask:0xf
	s_and_saveexec_b64 s[16:17], s[48:49]
	s_cbranch_execz .LBB0_726
	s_waitcnt vmcnt(4)
	v_pk_fma_f32 v[40:41], v[82:83], v[40:41], v[94:95]
	v_pk_fma_f32 v[32:33], v[84:85], v[32:33], v[96:97]
	v_pk_fma_f32 v[38:39], v[86:87], v[38:39], v[40:41]
	v_pk_fma_f32 v[30:31], v[88:89], v[30:31], v[32:33]
	v_pk_fma_f32 v[38:39], v[22:23], v[90:91], v[38:39]
	v_pk_fma_f32 v[30:31], v[24:25], v[92:93], v[30:31]
	v_mul_f32_e32 v0, 0xbfb8aa3b, v38
	v_mul_f32_e32 v40, 0xbfb8aa3b, v39
	v_exp_f32_e32 v0, v0
	v_exp_f32_e32 v40, v40
	s_waitcnt vmcnt(6)
	v_pk_fma_f32 v[36:37], v[66:67], v[36:37], v[78:79]
	v_mul_f32_e32 v32, 0xbfb8aa3b, v31
	v_add_f32_e32 v0, 1.0, v0
	v_add_f32_e32 v41, 1.0, v40
	v_rcp_f32_e32 v40, v0
	v_rcp_f32_e32 v41, v41
	v_mul_f32_e32 v0, 0xbfb8aa3b, v30
	v_exp_f32_e32 v0, v0
	v_pk_fma_f32 v[34:35], v[70:71], v[34:35], v[36:37]
	v_pk_mul_f32 v[36:37], v[38:39], v[40:41]
	v_exp_f32_e32 v38, v32
	v_pk_fma_f32 v[34:35], v[18:19], v[74:75], v[34:35]
	v_add_f32_e32 v0, 1.0, v0
	v_pk_mul_f32 v[32:33], v[34:35], v[36:37]
	v_rcp_f32_e32 v34, v0
	v_add_f32_e32 v0, 1.0, v38
	v_rcp_f32_e32 v35, v0
	v_pk_fma_f32 v[28:29], v[68:69], v[28:29], v[80:81]
	s_nop 0
	v_pk_fma_f32 v[26:27], v[72:73], v[26:27], v[28:29]
	v_pk_mul_f32 v[28:29], v[30:31], v[34:35]
	v_pk_fma_f32 v[26:27], v[20:21], v[76:77], v[26:27]
	s_nop 0
	v_pk_mul_f32 v[26:27], v[26:27], v[28:29]
	v_cvt_pk_bf16_f32 v28, v32, v33
	v_cvt_pk_bf16_f32 v29, v26, v27
	v_mov_b64_e32 v[26:27], s[12:13]
	v_mad_u64_u32 v[26:27], s[18:19], v108, s60, v[26:27]
	v_mad_i32_i24 v27, v109, s60, v27
	v_lshl_add_u64 v[26:27], v[202:203], 1, v[26:27]
	global_store_dwordx2 v[26:27], v[28:29], off offset:8
; __device__ __forceinline__ unsigned cvt_pk_bf16(float lo, float hi) { const f32x2_t v = {lo, hi}; const bf16x2_t b = __builtin_convertvector(v, bf16x2_t); return __builtin_bit_cast(unsigned, b); }
; template <int N> __device__ __forceinline__ float dpp_ror(float v) { return __builtin_bit_cast(float, __builtin_amdgcn_update_dpp(0, __builtin_bit_cast(int, v), 0x120 + N, 0xf, 0xf, false)); }
;     __device__ __forceinline__ void operator()(const Acc& acc, const Unit& u, int wr, int wc, int fr, int fq) const {
;     ...
;                 for (int m = 0; m < 4; ++m) {
;                     const int rt = ai * 128 + wr * 64 + m * 16 + fr;
;                     const f32x4 g = acc[ai][0][m][n], up = acc[ai][1][m][n];
;                     const f32x4 gp = (m == 0) ? hg : acc[ai][0][m == 0 ? 0 : m - 1][n], upp = (m == 0) ? hu : acc[ai][1][m == 0 ? 0 : m - 1][n];
;                     f32x4 g1, g2, u1, u2;
; #pragma unroll
;                     for (int j = 0; j < 4; ++j) {
;                         g1[j] = dpp_ror<1>((fr == 15) ? gp[j] : g[j]); g2[j] = dpp_ror<2>((fr >= 14) ? gp[j] : g[j]);
;                         u1[j] = dpp_ror<1>((fr == 15) ? upp[j] : up[j]); u2[j] = dpp_ror<2>((fr >= 14) ? upp[j] : up[j]);
;                     }
;                     const f32x4 hcg = gb + gw0 * g2 + gw1 * g1 + gw2 * g, hcu = ub + uw0 * u2 + uw1 * u1 + uw2 * up;
;                     f32x4 a;
; #pragma unroll
;                     for (int j = 0; j < 4; ++j) a[j] = hcg[j] * __builtin_amdgcn_rcpf(1.f + __builtin_amdgcn_exp2f(-1.4426950408889634f * hcg[j])) * hcu[j];
;                     if (rt >= 2) { u32x2 w; w.x = cvt_pk_bf16(a[0], a[1]); w.y = cvt_pk_bf16(a[2], a[3]); *(u32x2*)(act + ((size_t)u.pm * 256 + rt) * DFF + ch) = w; }
.LBB0_726:
	s_or_b64 exec, exec, s[16:17]
	v_cndmask_b32_e64 v0, v14, v22, s[42:43]
	v_cndmask_b32_e64 v244, v14, v22, s[40:41]
	v_cndmask_b32_e64 v245, v10, v18, s[42:43]
	v_mov_b32_dpp v30, v0 row_ror:1 row_mask:0xf bank_mask:0xf
	v_mov_b32_dpp v32, v244 row_ror:2 row_mask:0xf bank_mask:0xf
	v_mov_b32_dpp v26, v245 row_ror:1 row_mask:0xf bank_mask:0xf
	v_cndmask_b32_e64 v0, v10, v18, s[40:41]
	v_cndmask_b32_e64 v244, v15, v23, s[42:43]
	v_cndmask_b32_e64 v245, v15, v23, s[40:41]
	v_mov_b32_dpp v28, v0 row_ror:2 row_mask:0xf bank_mask:0xf
	v_mov_b32_dpp v31, v244 row_ror:1 row_mask:0xf bank_mask:0xf
	v_mov_b32_dpp v33, v245 row_ror:2 row_mask:0xf bank_mask:0xf
	v_cndmask_b32_e64 v0, v11, v19, s[42:43]
	v_cndmask_b32_e64 v244, v11, v19, s[40:41]
	v_cndmask_b32_e64 v245, v16, v24, s[42:43]
	v_mov_b32_dpp v27, v0 row_ror:1 row_mask:0xf bank_mask:0xf
	v_mov_b32_dpp v29, v244 row_ror:2 row_mask:0xf bank_mask:0xf
	v_mov_b32_dpp v22, v245 row_ror:1 row_mask:0xf bank_mask:0xf
	v_cndmask_b32_e64 v0, v16, v24, s[40:41]
	v_cndmask_b32_e64 v244, v12, v20, s[42:43]
	v_cndmask_b32_e64 v245, v12, v20, s[40:41]
	v_mov_b32_dpp v24, v0 row_ror:2 row_mask:0xf bank_mask:0xf
	v_mov_b32_dpp v18, v244 row_ror:1 row_mask:0xf bank_mask:0xf
	v_mov_b32_dpp v20, v245 row_ror:2 row_mask:0xf bank_mask:0xf
	v_cndmask_b32_e64 v0, v17, v25, s[42:43]
	v_cndmask_b32_e64 v244, v17, v25, s[40:41]
	v_cndmask_b32_e64 v245, v13, v21, s[42:43]
	v_mov_b32_dpp v23, v0 row_ror:1 row_mask:0xf bank_mask:0xf
	v_mov_b32_dpp v25, v244 row_ror:2 row_mask:0xf bank_mask:0xf
	v_mov_b32_dpp v19, v245 row_ror:1 row_mask:0xf bank_mask:0xf
	v_cndmask_b32_e64 v0, v13, v21, s[40:41]
	s_nop 1
	v_mov_b32_dpp v21, v0 row_ror:2 row_mask:0xf bank_mask:0xf
	s_and_saveexec_b64 s[16:17], s[50:51]
	s_cbranch_execz .LBB0_728
	s_waitcnt vmcnt(4)
	v_pk_fma_f32 v[32:33], v[82:83], v[32:33], v[94:95]
	v_pk_fma_f32 v[24:25], v[84:85], v[24:25], v[96:97]
	v_pk_fma_f32 v[30:31], v[86:87], v[30:31], v[32:33]
	v_pk_fma_f32 v[22:23], v[88:89], v[22:23], v[24:25]
	v_pk_fma_f32 v[30:31], v[14:15], v[90:91], v[30:31]
	v_pk_fma_f32 v[22:23], v[16:17], v[92:93], v[22:23]
	v_mul_f32_e32 v0, 0xbfb8aa3b, v30
	v_mul_f32_e32 v32, 0xbfb8aa3b, v31
	v_exp_f32_e32 v0, v0
	v_exp_f32_e32 v32, v32
	s_waitcnt vmcnt(6)
	v_pk_fma_f32 v[28:29], v[66:67], v[28:29], v[78:79]
	v_mul_f32_e32 v24, 0xbfb8aa3b, v23
	v_add_f32_e32 v0, 1.0, v0
	v_add_f32_e32 v33, 1.0, v32
	v_rcp_f32_e32 v32, v0
	v_rcp_f32_e32 v33, v33
	v_mul_f32_e32 v0, 0xbfb8aa3b, v22
	v_exp_f32_e32 v0, v0
	v_pk_fma_f32 v[26:27], v[70:71], v[26:27], v[28:29]
	v_pk_mul_f32 v[28:29], v[30:31], v[32:33]
	v_exp_f32_e32 v30, v24
	v_pk_fma_f32 v[26:27], v[10:11], v[74:75], v[26:27]
	v_add_f32_e32 v0, 1.0, v0
	v_pk_mul_f32 v[24:25], v[26:27], v[28:29]
	v_rcp_f32_e32 v26, v0
	v_add_f32_e32 v0, 1.0, v30
	v_rcp_f32_e32 v27, v0
	v_pk_fma_f32 v[20:21], v[68:69], v[20:21], v[80:81]
	s_nop 0
	v_pk_fma_f32 v[18:19], v[72:73], v[18:19], v[20:21]
	v_pk_mul_f32 v[20:21], v[22:23], v[26:27]
	v_pk_fma_f32 v[18:19], v[12:13], v[76:77], v[18:19]
	s_nop 0
	v_pk_mul_f32 v[18:19], v[18:19], v[20:21]
	v_cvt_pk_bf16_f32 v20, v24, v25
	v_cvt_pk_bf16_f32 v21, v18, v19
	v_mov_b64_e32 v[18:19], s[12:13]
	v_mad_u64_u32 v[18:19], s[18:19], v110, s60, v[18:19]
	v_mad_i32_i24 v19, v111, s60, v19
	v_lshl_add_u64 v[18:19], v[202:203], 1, v[18:19]
	global_store_dwordx2 v[18:19], v[20:21], off offset:8
.LBB0_728:
	s_or_b64 exec, exec, s[16:17]
	v_cndmask_b32_e64 v0, v6, v14, s[42:43]
	v_cndmask_b32_e64 v244, v6, v14, s[40:41]
	v_cndmask_b32_e64 v245, v2, v10, s[42:43]
	v_mov_b32_dpp v22, v0 row_ror:1 row_mask:0xf bank_mask:0xf
	v_mov_b32_dpp v24, v244 row_ror:2 row_mask:0xf bank_mask:0xf
	v_mov_b32_dpp v18, v245 row_ror:1 row_mask:0xf bank_mask:0xf
	v_cndmask_b32_e64 v0, v2, v10, s[40:41]
	v_cndmask_b32_e64 v244, v7, v15, s[42:43]
	v_cndmask_b32_e64 v245, v7, v15, s[40:41]
	v_mov_b32_dpp v20, v0 row_ror:2 row_mask:0xf bank_mask:0xf
	v_mov_b32_dpp v23, v244 row_ror:1 row_mask:0xf bank_mask:0xf
	v_mov_b32_dpp v25, v245 row_ror:2 row_mask:0xf bank_mask:0xf
	v_cndmask_b32_e64 v0, v3, v11, s[42:43]
	v_cndmask_b32_e64 v244, v3, v11, s[40:41]
	v_cndmask_b32_e64 v245, v8, v16, s[42:43]
	v_mov_b32_dpp v19, v0 row_ror:1 row_mask:0xf bank_mask:0xf
	v_mov_b32_dpp v21, v244 row_ror:2 row_mask:0xf bank_mask:0xf
	v_mov_b32_dpp v14, v245 row_ror:1 row_mask:0xf bank_mask:0xf
	v_cndmask_b32_e64 v0, v8, v16, s[40:41]
	v_cndmask_b32_e64 v244, v4, v12, s[42:43]
	v_cndmask_b32_e64 v245, v4, v12, s[40:41]
	v_mov_b32_dpp v16, v0 row_ror:2 row_mask:0xf bank_mask:0xf
	v_mov_b32_dpp v10, v244 row_ror:1 row_mask:0xf bank_mask:0xf
	v_mov_b32_dpp v12, v245 row_ror:2 row_mask:0xf bank_mask:0xf
	v_cndmask_b32_e64 v0, v9, v17, s[42:43]
	v_cndmask_b32_e64 v244, v9, v17, s[40:41]
	v_cndmask_b32_e64 v245, v5, v13, s[42:43]
	v_mov_b32_dpp v15, v0 row_ror:1 row_mask:0xf bank_mask:0xf
	v_mov_b32_dpp v17, v244 row_ror:2 row_mask:0xf bank_mask:0xf
	v_mov_b32_dpp v11, v245 row_ror:1 row_mask:0xf bank_mask:0xf
	v_cndmask_b32_e64 v0, v5, v13, s[40:41]
	s_nop 1
	v_mov_b32_dpp v13, v0 row_ror:2 row_mask:0xf bank_mask:0xf
	s_and_saveexec_b64 s[16:17], s[52:53]
	s_cbranch_execz .LBB0_730
	s_waitcnt vmcnt(4)
	v_pk_fma_f32 v[24:25], v[82:83], v[24:25], v[94:95]
	v_pk_fma_f32 v[16:17], v[84:85], v[16:17], v[96:97]
	v_pk_fma_f32 v[22:23], v[86:87], v[22:23], v[24:25]
	v_pk_fma_f32 v[14:15], v[88:89], v[14:15], v[16:17]
	v_pk_fma_f32 v[6:7], v[6:7], v[90:91], v[22:23]
	v_pk_fma_f32 v[8:9], v[8:9], v[92:93], v[14:15]
	v_mul_f32_e32 v0, 0xbfb8aa3b, v6
	v_exp_f32_e32 v0, v0
	v_mul_f32_e32 v22, 0xbfb8aa3b, v7
	v_exp_f32_e32 v22, v22
	v_mul_f32_e32 v14, 0xbfb8aa3b, v9
	v_add_f32_e32 v0, 1.0, v0
	v_exp_f32_e32 v14, v14
	v_add_f32_e32 v23, 1.0, v22
	v_rcp_f32_e32 v22, v0
	v_mul_f32_e32 v0, 0xbfb8aa3b, v8
	v_rcp_f32_e32 v23, v23
	v_exp_f32_e32 v0, v0
	s_waitcnt vmcnt(6)
	v_pk_fma_f32 v[20:21], v[66:67], v[20:21], v[78:79]
	v_pk_fma_f32 v[12:13], v[68:69], v[12:13], v[80:81]
	v_pk_fma_f32 v[18:19], v[70:71], v[18:19], v[20:21]
	v_pk_mul_f32 v[6:7], v[6:7], v[22:23]
	v_pk_fma_f32 v[2:3], v[2:3], v[74:75], v[18:19]
	v_add_f32_e32 v0, 1.0, v0
	v_pk_mul_f32 v[2:3], v[2:3], v[6:7]
	v_rcp_f32_e32 v6, v0
	v_add_f32_e32 v0, 1.0, v14
	v_rcp_f32_e32 v7, v0
	v_pk_fma_f32 v[10:11], v[72:73], v[10:11], v[12:13]
	v_cvt_pk_bf16_f32 v2, v2, v3
	v_pk_fma_f32 v[4:5], v[4:5], v[76:77], v[10:11]
	v_pk_mul_f32 v[6:7], v[8:9], v[6:7]
	s_nop 0
	v_pk_mul_f32 v[4:5], v[4:5], v[6:7]
	s_nop 0
	v_cvt_pk_bf16_f32 v3, v4, v5
	v_mov_b64_e32 v[4:5], s[12:13]
	v_mad_u64_u32 v[4:5], s[18:19], v148, s60, v[4:5]
	v_mad_i32_i24 v5, v149, s60, v5
	v_lshl_add_u64 v[4:5], v[202:203], 1, v[4:5]
	global_store_dwordx2 v[4:5], v[2:3], off offset:8
